# v28 + SwiGLU GEMMs clear the next tile's accumulators with 8 matrix-pipe ops inside the epilogue instead of 64 v_mov_b64 after it
# speedup vs baseline: 1.0612x; 1.0001x over previous
; template <class Epi>
; __device__ __forceinline__ void gemm_phase(LAS unsigned char* lds, const Gemm g, const Sched& S, const Epi& E) {
;     ...
; #pragma unroll
;         for (int a = 0; a < 2; ++a)
; #pragma unroll
;             for (int b = 0; b < 2; ++b)
; #pragma unroll
;                 for (int m = 0; m < 4; ++m)
; #pragma unroll
;                     for (int n = 0; n < 2; ++n) acc[a][b][m][n] = (f32x4){0.f, 0.f, 0.f, 0.f};
;         cur = nxt; cA = nA; cB = nB; ++ui;
.LBB0_173:
	s_mov_b32 s57, s16
	s_mov_b32 s8, s18
	s_mov_b64 s[10:11], s[22:23]
	s_mov_b32 s56, s50
	s_andn2_b64 vcc, exec, s[4:5]
	s_mov_b64 s[24:25], s[20:21]
	s_cbranch_vccz .LBB0_180

; #define PG8_STAGE(bufoff, gbase, voff) do { _Pragma("unroll") for (int _i = 0; _i < 2; ++_i) \
;         __builtin_amdgcn_global_load_lds((const unsigned*)((const char*)(gbase) + (voff)[_i]), (LAS unsigned*)(lds + (bufoff) + ldsw + _i * 8192), 16, 0, 0); } while (0)
; #define PG8_LDA(dst, b, h) do { _Pragma("unroll") for (int m = 0; m < 4; ++m) _Pragma("unroll") for (int k = 0; k < 2; ++k) dst[m][k] = *(const LAS bf16x8*)(lds + PG8_SA(b, h) + aoff + m * 2048 + k * 1024); } while (0)
; #define PG8_LDB(dst, b, h) do { _Pragma("unroll") for (int n = 0; n < 2; ++n) _Pragma("unroll") for (int k = 0; k < 2; ++k) dst[n][k] = *(const LAS bf16x8*)(lds + PG8_SB(b, h) + boff + n * 2048 + k * 1024); } while (0)
; #define PG8_MMA(ai, bj, At, Bt) do { __builtin_amdgcn_s_setprio(1); _Pragma("unroll") for (int m = 0; m < 4; ++m) _Pragma("unroll") for (int n = 0; n < 2; ++n) _Pragma("unroll") for (int k = 0; k < 2; ++k) \
;         acc[ai][bj][m][n] = __builtin_amdgcn_mfma_f32_16x16x32_bf16(Bt[n][k], At[m][k], acc[ai][bj][m][n], 0, 0, 0); __builtin_amdgcn_s_setprio(0); } while (0)
; #define PG8_WAIT_L(n) asm volatile("s_waitcnt lgkmcnt(" #n ")" ::: "memory")
; #define PG8_BAR __builtin_amdgcn_s_barrier()
; #define PG8_SCHED __builtin_amdgcn_sched_barrier(0)
; template <class Epi>
; __device__ __forceinline__ void gemm_phase(LAS unsigned char* lds, const Gemm g, const Sched& S, const Epi& E) {
;     ...
;             PG8_LDB(B0, 0, 0); PG8_SCHED; PG8_LDA(At, 0, 0); PG8_STAGE(PG8_SA(1, 1), a1 + hstepA, voffA);
;             PG8_WAIT_L(8); PG8_BAR; PG8_WAIT_L(0); PG8_MMA(0, 0, At, B0); PG8_BAR; PG8_SCHED;
;             PG8_LDB(B1, 0, 1); PG8_STAGE(PG8_SB(0, 0), b2, voffB);
;             PG8_BAR; PG8_WAIT_L(0); PG8_MMA(0, 1, At, B1); PG8_BAR;
;             PG8_LDA(At, 0, 1); PG8_STAGE(PG8_SA(0, 0), a2, voffA);
;             PG8_BAR; PG8_WAIT_L(0); PG8_MMA(1, 0, At, B0); PG8_BAR; PG8_SCHED;
.LBB0_177:
	v_add_u32_e32 v162, s62, v148
	s_add_u32 s38, s10, s24
	ds_read_b128 v[150:153], v162
	ds_read_b128 v[154:157], v162 offset:1024
	ds_read_b128 v[158:161], v162 offset:2048
	ds_read_b128 v[162:165], v162 offset:3072
	s_addc_u32 s39, s11, s25
	s_add_u32 s38, s38, 0x100
	s_addc_u32 s39, s39, 0
	s_add_u32 s71, s9, s24
	s_addc_u32 s80, s51, s25
	s_cmpk_eq_i32 s24, 0xf00
	s_cselect_b32 s53, s19, s39
	s_cselect_b32 s52, s66, s38
	s_cselect_b32 s39, s17, s80
	s_cselect_b32 s38, s67, s71
	v_lshl_add_u64 v[190:191], v[144:145], 0, s[24:25]
	s_add_i32 m0, s35, 0xc000
	ds_read_b128 v[166:169], v149
	ds_read_b128 v[170:173], v149 offset:1024
	ds_read_b128 v[174:177], v149 offset:2048
	ds_read_b128 v[178:181], v149 offset:3072
	ds_read_b128 v[182:185], v149 offset:4096
	ds_read_b128 v[186:189], v149 offset:5120
	ds_read_b128 v[194:197], v149 offset:6144
	ds_read_b128 v[198:201], v149 offset:7168
	global_load_lds_dwordx4 v[190:191], off
	v_lshl_add_u64 v[190:191], v[146:147], 0, s[24:25]
	s_add_i32 m0, s35, 0xe000
	s_nop 0
	global_load_lds_dwordx4 v[190:191], off
	s_waitcnt lgkmcnt(8)
	s_barrier
	s_waitcnt lgkmcnt(0)
	s_setprio 1
	s_waitcnt lgkmcnt(0)
	v_mfma_f32_16x16x32_bf16 v[124:127], v[150:153], v[166:169], v[124:127]
	v_mfma_f32_16x16x32_bf16 v[120:123], v[158:161], v[166:169], v[120:123]
	v_mfma_f32_16x16x32_bf16 v[116:119], v[150:153], v[174:177], v[116:119]
	v_mfma_f32_16x16x32_bf16 v[112:115], v[158:161], v[174:177], v[112:115]
	v_mfma_f32_16x16x32_bf16 v[108:111], v[150:153], v[182:185], v[108:111]
	v_mfma_f32_16x16x32_bf16 v[104:107], v[158:161], v[182:185], v[104:107]
	v_mfma_f32_16x16x32_bf16 v[100:103], v[150:153], v[194:197], v[100:103]
	v_mfma_f32_16x16x32_bf16 v[96:99], v[158:161], v[194:197], v[96:99]
	v_mfma_f32_16x16x32_bf16 v[124:127], v[154:157], v[170:173], v[124:127]
	v_mfma_f32_16x16x32_bf16 v[120:123], v[162:165], v[170:173], v[120:123]
	v_mfma_f32_16x16x32_bf16 v[116:119], v[154:157], v[178:181], v[116:119]
	v_mfma_f32_16x16x32_bf16 v[112:115], v[162:165], v[178:181], v[112:115]
	v_mfma_f32_16x16x32_bf16 v[108:111], v[154:157], v[186:189], v[108:111]
	v_mfma_f32_16x16x32_bf16 v[104:107], v[162:165], v[186:189], v[104:107]
	v_mfma_f32_16x16x32_bf16 v[100:103], v[154:157], v[198:201], v[100:103]
	v_mfma_f32_16x16x32_bf16 v[96:99], v[162:165], v[198:201], v[96:99]
	s_setprio 0
	s_barrier
	v_add_u32_e32 v190, s63, v148
	s_add_i32 s71, s62, s1
	ds_read_b128 v[202:205], v190
	ds_read_b128 v[206:209], v190 offset:1024
	ds_read_b128 v[210:213], v190 offset:2048
	ds_read_b128 v[214:217], v190 offset:3072
	v_lshl_add_u64 v[190:191], s[38:39], 0, v[130:131]
	s_mov_b32 m0, s71
	v_lshl_add_u64 v[218:219], s[38:39], 0, v[128:129]
	global_load_lds_dwordx4 v[190:191], off
	s_add_i32 m0, s71, 0x2000
	s_nop 0
	global_load_lds_dwordx4 v[218:219], off
	s_barrier
	s_waitcnt lgkmcnt(0)
	s_setprio 1
	s_waitcnt lgkmcnt(0)
	v_mfma_f32_16x16x32_bf16 v[92:95], v[202:205], v[166:169], v[92:95]
	v_mfma_f32_16x16x32_bf16 v[88:91], v[210:213], v[166:169], v[88:91]
	v_mfma_f32_16x16x32_bf16 v[84:87], v[202:205], v[174:177], v[84:87]
	v_mfma_f32_16x16x32_bf16 v[80:83], v[210:213], v[174:177], v[80:83]
	v_mfma_f32_16x16x32_bf16 v[76:79], v[202:205], v[182:185], v[76:79]
	v_mfma_f32_16x16x32_bf16 v[72:75], v[210:213], v[182:185], v[72:75]
	v_mfma_f32_16x16x32_bf16 v[68:71], v[202:205], v[194:197], v[68:71]
	v_mfma_f32_16x16x32_bf16 v[64:67], v[210:213], v[194:197], v[64:67]
	v_mfma_f32_16x16x32_bf16 v[92:95], v[206:209], v[170:173], v[92:95]
	v_mfma_f32_16x16x32_bf16 v[88:91], v[214:217], v[170:173], v[88:91]
	v_mfma_f32_16x16x32_bf16 v[84:87], v[206:209], v[178:181], v[84:87]
	v_mfma_f32_16x16x32_bf16 v[80:83], v[214:217], v[178:181], v[80:83]
	v_mfma_f32_16x16x32_bf16 v[76:79], v[206:209], v[186:189], v[76:79]
	v_mfma_f32_16x16x32_bf16 v[72:75], v[214:217], v[186:189], v[72:75]
	v_mfma_f32_16x16x32_bf16 v[68:71], v[206:209], v[198:201], v[68:71]
	v_mfma_f32_16x16x32_bf16 v[64:67], v[214:217], v[198:201], v[64:67]
	s_setprio 0
	s_mov_b32 m0, s35
	v_lshl_add_u64 v[220:221], s[52:53], 0, v[130:131]
	s_barrier
	ds_read_b128 v[166:169], v149 offset:16384
	ds_read_b128 v[170:173], v149 offset:17408
	ds_read_b128 v[174:177], v149 offset:18432
	ds_read_b128 v[178:181], v149 offset:19456
	ds_read_b128 v[182:185], v149 offset:20480
	ds_read_b128 v[186:189], v149 offset:21504
	ds_read_b128 v[194:197], v149 offset:22528
	ds_read_b128 v[198:201], v149 offset:23552
	global_load_lds_dwordx4 v[220:221], off
	v_lshl_add_u64 v[222:223], s[52:53], 0, v[128:129]
	s_mov_b32 m0, s43
	s_nop 0
	global_load_lds_dwordx4 v[222:223], off
	s_barrier
	s_waitcnt lgkmcnt(0)
	s_setprio 1
	s_waitcnt lgkmcnt(0)
	v_mfma_f32_16x16x32_bf16 v[60:63], v[150:153], v[166:169], v[60:63]
	v_mfma_f32_16x16x32_bf16 v[56:59], v[158:161], v[166:169], v[56:59]
	v_mfma_f32_16x16x32_bf16 v[52:55], v[150:153], v[174:177], v[52:55]
	v_mfma_f32_16x16x32_bf16 v[48:51], v[158:161], v[174:177], v[48:51]
	v_mfma_f32_16x16x32_bf16 v[44:47], v[150:153], v[182:185], v[44:47]
	v_mfma_f32_16x16x32_bf16 v[40:43], v[158:161], v[182:185], v[40:43]
	v_mfma_f32_16x16x32_bf16 v[36:39], v[150:153], v[194:197], v[36:39]
	v_mfma_f32_16x16x32_bf16 v[32:35], v[158:161], v[194:197], v[32:35]
	v_mfma_f32_16x16x32_bf16 v[60:63], v[154:157], v[170:173], v[60:63]
	v_mfma_f32_16x16x32_bf16 v[56:59], v[162:165], v[170:173], v[56:59]
	v_mfma_f32_16x16x32_bf16 v[52:55], v[154:157], v[178:181], v[52:55]
	v_mfma_f32_16x16x32_bf16 v[48:51], v[162:165], v[178:181], v[48:51]
	v_mfma_f32_16x16x32_bf16 v[44:47], v[154:157], v[186:189], v[44:47]
	v_mfma_f32_16x16x32_bf16 v[40:43], v[162:165], v[186:189], v[40:43]
	v_mfma_f32_16x16x32_bf16 v[36:39], v[154:157], v[198:201], v[36:39]
	v_mfma_f32_16x16x32_bf16 v[32:35], v[162:165], v[198:201], v[32:35]
	s_setprio 0
	s_barrier
; #define PG8_STAGE(bufoff, gbase, voff) do { _Pragma("unroll") for (int _i = 0; _i < 2; ++_i) \
;         __builtin_amdgcn_global_load_lds((const unsigned*)((const char*)(gbase) + (voff)[_i]), (LAS unsigned*)(lds + (bufoff) + ldsw + _i * 8192), 16, 0, 0); } while (0)
; #define PG8_LDA(dst, b, h) do { _Pragma("unroll") for (int m = 0; m < 4; ++m) _Pragma("unroll") for (int k = 0; k < 2; ++k) dst[m][k] = *(const LAS bf16x8*)(lds + PG8_SA(b, h) + aoff + m * 2048 + k * 1024); } while (0)
; #define PG8_LDB(dst, b, h) do { _Pragma("unroll") for (int n = 0; n < 2; ++n) _Pragma("unroll") for (int k = 0; k < 2; ++k) dst[n][k] = *(const LAS bf16x8*)(lds + PG8_SB(b, h) + boff + n * 2048 + k * 1024); } while (0)
; #define PG8_MMA(ai, bj, At, Bt) do { __builtin_amdgcn_s_setprio(1); _Pragma("unroll") for (int m = 0; m < 4; ++m) _Pragma("unroll") for (int n = 0; n < 2; ++n) _Pragma("unroll") for (int k = 0; k < 2; ++k) \
;         acc[ai][bj][m][n] = __builtin_amdgcn_mfma_f32_16x16x32_bf16(Bt[n][k], At[m][k], acc[ai][bj][m][n], 0, 0, 0); __builtin_amdgcn_s_setprio(0); } while (0)
; #define PG8_WAIT_V(n) asm volatile("s_waitcnt vmcnt(" #n ")" ::: "memory")
; #define PG8_WAIT_L(n) asm volatile("s_waitcnt lgkmcnt(" #n ")" ::: "memory")
; #define PG8_BAR __builtin_amdgcn_s_barrier()
; #define PG8_SCHED __builtin_amdgcn_sched_barrier(0)
; template <class Epi>
; __device__ __forceinline__ void gemm_phase(LAS unsigned char* lds, const Gemm g, const Sched& S, const Epi& E) {
;     ...
;             PG8_STAGE(PG8_SB(0, 1), b2 + hstepB, voffB);
;             PG8_WAIT_V(6); PG8_BAR; PG8_MMA(1, 1, At, B1); PG8_BAR;
;             PG8_LDB(B0, 1, 0); PG8_SCHED; PG8_LDA(At, 1, 0); PG8_STAGE(PG8_SA(0, 1), a2 + hstepA, voffA);
;             PG8_WAIT_L(8); PG8_BAR; PG8_WAIT_L(0); PG8_MMA(0, 0, At, B0); PG8_BAR; PG8_SCHED;
;             PG8_LDB(B1, 1, 1); PG8_STAGE(PG8_SB(1, 0), b3, voffB);
;             PG8_BAR; PG8_WAIT_L(0); PG8_MMA(0, 1, At, B1); PG8_BAR;
;             PG8_LDA(At, 1, 1); PG8_STAGE(PG8_SA(1, 0), a3, voffA);
;             PG8_BAR; PG8_WAIT_L(0); PG8_MMA(1, 0, At, B0); PG8_BAR; PG8_SCHED;
	s_add_u32 s80, s38, 0x80000
	s_addc_u32 s81, s39, 0
	s_add_i32 s71, s63, s1
	v_lshl_add_u64 v[150:151], s[80:81], 0, v[130:131]
	s_mov_b32 m0, s71
	s_nop 0
	global_load_lds_dwordx4 v[150:151], off
	v_lshl_add_u64 v[150:151], s[80:81], 0, v[128:129]
	s_add_i32 m0, s71, 0x2000
	s_nop 0
	global_load_lds_dwordx4 v[150:151], off
	s_waitcnt vmcnt(6)
	s_barrier
	s_setprio 1
	v_mfma_f32_16x16x32_bf16 v[28:31], v[202:205], v[166:169], v[28:31]
	v_mfma_f32_16x16x32_bf16 v[24:27], v[210:213], v[166:169], v[24:27]
	v_mfma_f32_16x16x32_bf16 v[20:23], v[202:205], v[174:177], v[20:23]
	v_mfma_f32_16x16x32_bf16 v[16:19], v[210:213], v[174:177], v[16:19]
	v_mfma_f32_16x16x32_bf16 v[12:15], v[202:205], v[182:185], v[12:15]
	v_mfma_f32_16x16x32_bf16 v[8:11], v[210:213], v[182:185], v[8:11]
	v_mfma_f32_16x16x32_bf16 v[4:7], v[202:205], v[194:197], v[4:7]
	v_mfma_f32_16x16x32_bf16 v[0:3], v[210:213], v[194:197], v[0:3]
	v_mfma_f32_16x16x32_bf16 v[28:31], v[206:209], v[170:173], v[28:31]
	v_mfma_f32_16x16x32_bf16 v[24:27], v[214:217], v[170:173], v[24:27]
	v_mfma_f32_16x16x32_bf16 v[20:23], v[206:209], v[178:181], v[20:23]
	v_mfma_f32_16x16x32_bf16 v[16:19], v[214:217], v[178:181], v[16:19]
	v_mfma_f32_16x16x32_bf16 v[12:15], v[206:209], v[186:189], v[12:15]
	v_mfma_f32_16x16x32_bf16 v[8:11], v[214:217], v[186:189], v[8:11]
	v_mfma_f32_16x16x32_bf16 v[4:7], v[206:209], v[198:201], v[4:7]
	v_mfma_f32_16x16x32_bf16 v[0:3], v[214:217], v[198:201], v[0:3]
	s_setprio 0
	s_add_i32 s71, 0, 0x18000
	v_add_u32_e32 v162, s71, v148
	s_barrier
	ds_read_b128 v[150:153], v162
	ds_read_b128 v[154:157], v162 offset:1024
	ds_read_b128 v[158:161], v162 offset:2048
	ds_read_b128 v[162:165], v162 offset:3072
	s_add_u32 s52, s52, 0x80000
	s_addc_u32 s53, s53, 0
	s_mov_b32 m0, s54
	v_lshl_add_u64 v[202:203], s[52:53], 0, v[130:131]
	ds_read_b128 v[166:169], v149 offset:32768
	ds_read_b128 v[170:173], v149 offset:33792
	ds_read_b128 v[174:177], v149 offset:34816
	ds_read_b128 v[178:181], v149 offset:35840
	ds_read_b128 v[182:185], v149 offset:36864
	ds_read_b128 v[186:189], v149 offset:37888
	ds_read_b128 v[194:197], v149 offset:38912
	ds_read_b128 v[198:201], v149 offset:39936
	global_load_lds_dwordx4 v[202:203], off
	v_lshl_add_u64 v[202:203], s[52:53], 0, v[128:129]
	s_mov_b32 m0, s55
	s_nop 0
	global_load_lds_dwordx4 v[202:203], off
	s_waitcnt lgkmcnt(8)
	s_barrier
	s_waitcnt lgkmcnt(0)
	s_setprio 1
	s_waitcnt lgkmcnt(0)
	v_mfma_f32_16x16x32_bf16 v[124:127], v[150:153], v[166:169], v[124:127]
	v_mfma_f32_16x16x32_bf16 v[120:123], v[158:161], v[166:169], v[120:123]
	v_mfma_f32_16x16x32_bf16 v[116:119], v[150:153], v[174:177], v[116:119]
	v_mfma_f32_16x16x32_bf16 v[112:115], v[158:161], v[174:177], v[112:115]
	v_mfma_f32_16x16x32_bf16 v[108:111], v[150:153], v[182:185], v[108:111]
	v_mfma_f32_16x16x32_bf16 v[104:107], v[158:161], v[182:185], v[104:107]
	v_mfma_f32_16x16x32_bf16 v[100:103], v[150:153], v[194:197], v[100:103]
	v_mfma_f32_16x16x32_bf16 v[96:99], v[158:161], v[194:197], v[96:99]
	v_mfma_f32_16x16x32_bf16 v[124:127], v[154:157], v[170:173], v[124:127]
	v_mfma_f32_16x16x32_bf16 v[120:123], v[162:165], v[170:173], v[120:123]
	v_mfma_f32_16x16x32_bf16 v[116:119], v[154:157], v[178:181], v[116:119]
	v_mfma_f32_16x16x32_bf16 v[112:115], v[162:165], v[178:181], v[112:115]
	v_mfma_f32_16x16x32_bf16 v[108:111], v[154:157], v[186:189], v[108:111]
	v_mfma_f32_16x16x32_bf16 v[104:107], v[162:165], v[186:189], v[104:107]
	v_mfma_f32_16x16x32_bf16 v[100:103], v[154:157], v[198:201], v[100:103]
	v_mfma_f32_16x16x32_bf16 v[96:99], v[162:165], v[198:201], v[96:99]
	s_setprio 0
	s_barrier
	s_add_i32 s52, 0, 0x1c000
	s_add_i32 s53, s71, s1
	v_add_u32_e32 v214, s52, v148
	v_lshl_add_u64 v[190:191], v[190:191], 0, s[14:15]
	s_mov_b32 m0, s53
	ds_read_b128 v[202:205], v214
	ds_read_b128 v[206:209], v214 offset:1024
	ds_read_b128 v[210:213], v214 offset:2048
	ds_read_b128 v[214:217], v214 offset:3072
	global_load_lds_dwordx4 v[190:191], off
	v_lshl_add_u64 v[190:191], v[218:219], 0, s[14:15]
	s_add_i32 m0, s53, 0x2000
	s_nop 0
	global_load_lds_dwordx4 v[190:191], off
	s_barrier
	s_waitcnt lgkmcnt(0)
	s_setprio 1
	s_waitcnt lgkmcnt(0)
	v_mfma_f32_16x16x32_bf16 v[92:95], v[202:205], v[166:169], v[92:95]
	v_mfma_f32_16x16x32_bf16 v[88:91], v[210:213], v[166:169], v[88:91]
	v_mfma_f32_16x16x32_bf16 v[84:87], v[202:205], v[174:177], v[84:87]
	v_mfma_f32_16x16x32_bf16 v[80:83], v[210:213], v[174:177], v[80:83]
	v_mfma_f32_16x16x32_bf16 v[76:79], v[202:205], v[182:185], v[76:79]
	v_mfma_f32_16x16x32_bf16 v[72:75], v[210:213], v[182:185], v[72:75]
	v_mfma_f32_16x16x32_bf16 v[68:71], v[202:205], v[194:197], v[68:71]
	v_mfma_f32_16x16x32_bf16 v[64:67], v[210:213], v[194:197], v[64:67]
	v_mfma_f32_16x16x32_bf16 v[92:95], v[206:209], v[170:173], v[92:95]
	v_mfma_f32_16x16x32_bf16 v[88:91], v[214:217], v[170:173], v[88:91]
	v_mfma_f32_16x16x32_bf16 v[84:87], v[206:209], v[178:181], v[84:87]
	v_mfma_f32_16x16x32_bf16 v[80:83], v[214:217], v[178:181], v[80:83]
	v_mfma_f32_16x16x32_bf16 v[76:79], v[206:209], v[186:189], v[76:79]
	v_mfma_f32_16x16x32_bf16 v[72:75], v[214:217], v[186:189], v[72:75]
	v_mfma_f32_16x16x32_bf16 v[68:71], v[206:209], v[198:201], v[68:71]
	v_mfma_f32_16x16x32_bf16 v[64:67], v[214:217], v[198:201], v[64:67]
	s_setprio 0
	s_mov_b32 m0, s59
	v_lshl_add_u64 v[190:191], v[220:221], 0, s[14:15]
	s_barrier
	ds_read_b128 v[166:169], v149 offset:49152
	ds_read_b128 v[170:173], v149 offset:50176
	ds_read_b128 v[174:177], v149 offset:51200
	ds_read_b128 v[178:181], v149 offset:52224
	ds_read_b128 v[182:185], v149 offset:53248
	ds_read_b128 v[186:189], v149 offset:54272
	ds_read_b128 v[194:197], v149 offset:55296
	ds_read_b128 v[198:201], v149 offset:56320
	global_load_lds_dwordx4 v[190:191], off
	v_lshl_add_u64 v[190:191], v[222:223], 0, s[14:15]
	s_mov_b32 m0, s61
	s_nop 0
	global_load_lds_dwordx4 v[190:191], off
	s_barrier
; __device__ __forceinline__ unsigned cvt_pk_bf16(float lo, float hi) { unsigned r; asm volatile("v_cvt_pk_bf16_f32 %0, %1, %2" : "=v"(r) : "v"(lo), "v"(hi)); return r; }
; #define PG8_STAGE(bufoff, gbase, voff) do { _Pragma("unroll") for (int _i = 0; _i < 2; ++_i) \
;         __builtin_amdgcn_global_load_lds((const unsigned*)((const char*)(gbase) + (voff)[_i]), (LAS unsigned*)(lds + (bufoff) + ldsw + _i * 8192), 16, 0, 0); } while (0)
; #define PG8_MMA(ai, bj, At, Bt) do { __builtin_amdgcn_s_setprio(1); _Pragma("unroll") for (int m = 0; m < 4; ++m) _Pragma("unroll") for (int n = 0; n < 2; ++n) _Pragma("unroll") for (int k = 0; k < 2; ++k) \
;         acc[ai][bj][m][n] = __builtin_amdgcn_mfma_f32_16x16x32_bf16(Bt[n][k], At[m][k], acc[ai][bj][m][n], 0, 0, 0); __builtin_amdgcn_s_setprio(0); } while (0)
; #define PG8_WAIT_V(n) asm volatile("s_waitcnt vmcnt(" #n ")" ::: "memory")
; #define PG8_WAIT_L(n) asm volatile("s_waitcnt lgkmcnt(" #n ")" ::: "memory")
; #define PG8_BAR __builtin_amdgcn_s_barrier()
; #define PG8_SCHED __builtin_amdgcn_sched_barrier(0)
; template <class Epi>
; __device__ __forceinline__ void gemm_phase(LAS unsigned char* lds, const Gemm g, const Sched& S, const Epi& E) {
;     ...
;             PG8_BAR; PG8_WAIT_L(0); PG8_MMA(1, 0, At, B0); PG8_BAR; PG8_SCHED;
;             PG8_STAGE(PG8_SB(1, 1), b3 + hstepB, voffB);
;             PG8_WAIT_V(6); PG8_BAR; PG8_MMA(1, 1, At, B1); PG8_BAR;
;     __device__ __forceinline__ void operator()(AccRef acc, const Unit& u, int wr, int wc, int fr, int fq) const {
; #pragma unroll
;         for (int ai = 0; ai < 2; ++ai)
; #pragma unroll
;             for (int m = 0; m < 4; ++m) { const size_t row = (size_t)u.pm * 256 + ai * 128 + wr * 64 + m * 16 + fr; float o[8];
; #pragma unroll
;                 for (int bj = 0; bj < 2; ++bj) { const f32x4 gg = acc[ai][bj][m][0], uu = acc[ai][bj][m][1];
; #pragma unroll
;                     for (int j = 0; j < 4; ++j) o[4 * bj + j] = gg[j] * __builtin_amdgcn_rcpf(1.0f + __expf(-gg[j])) * uu[j]; }
;                 u32x4 w; w.x = cvt_pk_bf16(o[0], o[1]); w.y = cvt_pk_bf16(o[2], o[3]); w.z = cvt_pk_bf16(o[4], o[5]); w.w = cvt_pk_bf16(o[6], o[7]);
;                 *(u32x4*)(act + row * FF_ + (u.pn * 4 + wc) * 32 + 8 * fq) = w; }
	s_waitcnt lgkmcnt(0)
	s_setprio 1
	s_waitcnt lgkmcnt(0)
	v_mfma_f32_16x16x32_bf16 v[60:63], v[150:153], v[166:169], v[60:63]
	v_mfma_f32_16x16x32_bf16 v[56:59], v[158:161], v[166:169], v[56:59]
	v_mfma_f32_16x16x32_bf16 v[52:55], v[150:153], v[174:177], v[52:55]
	v_mfma_f32_16x16x32_bf16 v[48:51], v[158:161], v[174:177], v[48:51]
	v_mfma_f32_16x16x32_bf16 v[44:47], v[150:153], v[182:185], v[44:47]
	v_mfma_f32_16x16x32_bf16 v[40:43], v[158:161], v[182:185], v[40:43]
	v_mfma_f32_16x16x32_bf16 v[36:39], v[150:153], v[194:197], v[36:39]
	v_mfma_f32_16x16x32_bf16 v[32:35], v[158:161], v[194:197], v[32:35]
	v_mfma_f32_16x16x32_bf16 v[60:63], v[154:157], v[170:173], v[60:63]
	v_mfma_f32_16x16x32_bf16 v[56:59], v[162:165], v[170:173], v[56:59]
	v_mfma_f32_16x16x32_bf16 v[52:55], v[154:157], v[178:181], v[52:55]
	v_mfma_f32_16x16x32_bf16 v[48:51], v[162:165], v[178:181], v[48:51]
	v_mfma_f32_16x16x32_bf16 v[44:47], v[154:157], v[186:189], v[44:47]
	v_mfma_f32_16x16x32_bf16 v[40:43], v[162:165], v[186:189], v[40:43]
	v_mfma_f32_16x16x32_bf16 v[36:39], v[154:157], v[198:201], v[36:39]
	v_mfma_f32_16x16x32_bf16 v[32:35], v[162:165], v[198:201], v[32:35]
	s_setprio 0
	s_barrier
	s_add_u32 s38, s38, 0x80080
	s_addc_u32 s39, s39, 0
	s_add_i32 s52, s52, s1
	v_lshl_add_u64 v[150:151], s[38:39], 0, v[130:131]
	s_mov_b32 m0, s52
	s_nop 0
	global_load_lds_dwordx4 v[150:151], off
	v_lshl_add_u64 v[150:151], s[38:39], 0, v[128:129]
	s_add_i32 m0, s52, 0x2000
	s_nop 0
	global_load_lds_dwordx4 v[150:151], off
	s_waitcnt vmcnt(6)
	s_barrier
	s_setprio 1
	v_mfma_f32_16x16x32_bf16 v[28:31], v[202:205], v[166:169], v[28:31]
	v_mfma_f32_16x16x32_bf16 v[24:27], v[210:213], v[166:169], v[24:27]
	v_mfma_f32_16x16x32_bf16 v[20:23], v[202:205], v[174:177], v[20:23]
	v_mfma_f32_16x16x32_bf16 v[16:19], v[210:213], v[174:177], v[16:19]
	v_mfma_f32_16x16x32_bf16 v[12:15], v[202:205], v[182:185], v[12:15]
	v_mfma_f32_16x16x32_bf16 v[8:11], v[210:213], v[182:185], v[8:11]
	v_mfma_f32_16x16x32_bf16 v[4:7], v[202:205], v[194:197], v[4:7]
	v_mfma_f32_16x16x32_bf16 v[0:3], v[210:213], v[194:197], v[0:3]
	v_mfma_f32_16x16x32_bf16 v[28:31], v[206:209], v[170:173], v[28:31]
	v_mfma_f32_16x16x32_bf16 v[24:27], v[214:217], v[170:173], v[24:27]
	v_mfma_f32_16x16x32_bf16 v[20:23], v[206:209], v[178:181], v[20:23]
	v_mfma_f32_16x16x32_bf16 v[16:19], v[214:217], v[178:181], v[16:19]
	v_mfma_f32_16x16x32_bf16 v[12:15], v[206:209], v[186:189], v[12:15]
	v_mfma_f32_16x16x32_bf16 v[8:11], v[214:217], v[186:189], v[8:11]
	v_mfma_f32_16x16x32_bf16 v[4:7], v[206:209], v[198:201], v[4:7]
	v_mfma_f32_16x16x32_bf16 v[0:3], v[214:217], v[198:201], v[0:3]
	s_setprio 0
	s_add_i32 s70, s70, 2
	s_add_u32 s24, s24, 0x100
	s_addc_u32 s25, s25, 0
	s_cmp_gt_u32 s70, 29
	s_barrier
	s_cbranch_scc0 .LBB0_177
	v_mov_b32_e32 v170, 0xbfb8aa3b
	v_mov_b32_e32 v172, 1.0
	v_mov_b64_e32 v[176:177], 0
	v_mov_b64_e32 v[178:179], 0
	s_add_u32 s24, s9, 0xffffff00
	s_addc_u32 s25, s51, -1
	s_ashr_i32 s9, s8, 31
	s_lshl_b64 s[38:39], s[8:9], 8
	v_lshl_add_u64 v[144:145], v[134:135], 0, s[38:39]
	v_mov_b64_e32 v[146:147], s[44:45]
	v_mad_u64_u32 v[146:147], s[52:53], v144, s64, v[146:147]
	s_lshl_b32 s9, s57, 7
	v_mov_b32_e32 v144, v147
	s_or_b32 s38, s9, s58
	v_mad_u64_u32 v[144:145], s[52:53], v145, s64, v[144:145]
	s_ashr_i32 s39, s38, 31
	v_mov_b32_e32 v147, v144
	v_lshl_add_u64 v[144:145], s[38:39], 1, v[146:147]
	v_lshl_add_u64 v[144:145], v[144:145], 0, v[132:133]
	v_pk_mul_f32 v[162:163], v[124:125], v[170:171] op_sel_hi:[1,0]
	v_pk_mul_f32 v[164:165], v[126:127], v[170:171] op_sel_hi:[1,0]
	v_pk_mul_f32 v[166:167], v[92:93], v[170:171] op_sel_hi:[1,0]
	v_pk_mul_f32 v[168:169], v[94:95], v[170:171] op_sel_hi:[1,0]
	v_exp_f32_e32 v162, v162
	v_exp_f32_e32 v163, v163
	v_exp_f32_e32 v164, v164
	v_exp_f32_e32 v165, v165
	v_exp_f32_e32 v166, v166
	v_exp_f32_e32 v167, v167
	v_exp_f32_e32 v168, v168
	v_exp_f32_e32 v169, v169
	v_pk_add_f32 v[162:163], v[162:163], v[172:173] op_sel_hi:[1,0]
	v_pk_add_f32 v[164:165], v[164:165], v[172:173] op_sel_hi:[1,0]
	v_pk_add_f32 v[166:167], v[166:167], v[172:173] op_sel_hi:[1,0]
	v_pk_add_f32 v[168:169], v[168:169], v[172:173] op_sel_hi:[1,0]
	v_rcp_f32_e32 v162, v162
	v_rcp_f32_e32 v163, v163
	v_rcp_f32_e32 v164, v164
	v_rcp_f32_e32 v165, v165
	v_rcp_f32_e32 v166, v166
	v_rcp_f32_e32 v167, v167
	v_rcp_f32_e32 v168, v168
	v_rcp_f32_e32 v169, v169
	v_pk_mul_f32 v[162:163], v[124:125], v[162:163]
	v_pk_mul_f32 v[164:165], v[126:127], v[164:165]
	v_pk_mul_f32 v[166:167], v[92:93], v[166:167]
	v_pk_mul_f32 v[168:169], v[94:95], v[168:169]
	v_pk_mul_f32 v[162:163], v[120:121], v[162:163]
	v_pk_mul_f32 v[164:165], v[122:123], v[164:165]
	v_pk_mul_f32 v[166:167], v[88:89], v[166:167]
	v_pk_mul_f32 v[168:169], v[90:91], v[168:169]
	v_cvt_pk_bf16_f32 v150, v162, v163
	v_cvt_pk_bf16_f32 v151, v164, v165
	v_cvt_pk_bf16_f32 v152, v166, v167
	v_cvt_pk_bf16_f32 v153, v168, v169
	global_store_dwordx4 v[144:145], v[150:153], off
	s_mov_b32 s9, 0x2c000
	v_add_co_u32_e32 v146, vcc, s9, v144
	s_nop 0
	v_addc_co_u32_e32 v147, vcc, 0, v145, vcc
	v_pk_mul_f32 v[162:163], v[116:117], v[170:171] op_sel_hi:[1,0]
	v_pk_mul_f32 v[164:165], v[118:119], v[170:171] op_sel_hi:[1,0]
	v_pk_mul_f32 v[166:167], v[84:85], v[170:171] op_sel_hi:[1,0]
	v_pk_mul_f32 v[168:169], v[86:87], v[170:171] op_sel_hi:[1,0]
	v_exp_f32_e32 v162, v162
	v_exp_f32_e32 v163, v163
	v_exp_f32_e32 v164, v164
	v_exp_f32_e32 v165, v165
	v_exp_f32_e32 v166, v166
	v_exp_f32_e32 v167, v167
	v_exp_f32_e32 v168, v168
	v_exp_f32_e32 v169, v169
	v_pk_add_f32 v[162:163], v[162:163], v[172:173] op_sel_hi:[1,0]
	v_pk_add_f32 v[164:165], v[164:165], v[172:173] op_sel_hi:[1,0]
; __device__ __forceinline__ unsigned cvt_pk_bf16(float lo, float hi) { unsigned r; asm volatile("v_cvt_pk_bf16_f32 %0, %1, %2" : "=v"(r) : "v"(lo), "v"(hi)); return r; }
;     __device__ __forceinline__ void operator()(AccRef acc, const Unit& u, int wr, int wc, int fr, int fq) const {
;     ...
;         for (int ai = 0; ai < 2; ++ai)
; #pragma unroll
;             for (int m = 0; m < 4; ++m) { const size_t row = (size_t)u.pm * 256 + ai * 128 + wr * 64 + m * 16 + fr; float o[8];
; #pragma unroll
;                 for (int bj = 0; bj < 2; ++bj) { const f32x4 gg = acc[ai][bj][m][0], uu = acc[ai][bj][m][1];
; #pragma unroll
;                     for (int j = 0; j < 4; ++j) o[4 * bj + j] = gg[j] * __builtin_amdgcn_rcpf(1.0f + __expf(-gg[j])) * uu[j]; }
;                 u32x4 w; w.x = cvt_pk_bf16(o[0], o[1]); w.y = cvt_pk_bf16(o[2], o[3]); w.z = cvt_pk_bf16(o[4], o[5]); w.w = cvt_pk_bf16(o[6], o[7]);
;                 *(u32x4*)(act + row * FF_ + (u.pn * 4 + wc) * 32 + 8 * fq) = w; }
	v_pk_add_f32 v[166:167], v[166:167], v[172:173] op_sel_hi:[1,0]
	v_pk_add_f32 v[168:169], v[168:169], v[172:173] op_sel_hi:[1,0]
	v_rcp_f32_e32 v162, v162
	v_rcp_f32_e32 v163, v163
	v_rcp_f32_e32 v164, v164
	v_rcp_f32_e32 v165, v165
	v_rcp_f32_e32 v166, v166
	v_rcp_f32_e32 v167, v167
	v_rcp_f32_e32 v168, v168
	v_rcp_f32_e32 v169, v169
	v_pk_mul_f32 v[162:163], v[116:117], v[162:163]
	v_pk_mul_f32 v[164:165], v[118:119], v[164:165]
	v_pk_mul_f32 v[166:167], v[84:85], v[166:167]
	v_pk_mul_f32 v[168:169], v[86:87], v[168:169]
	v_pk_mul_f32 v[162:163], v[112:113], v[162:163]
	v_pk_mul_f32 v[164:165], v[114:115], v[164:165]
	v_pk_mul_f32 v[166:167], v[80:81], v[166:167]
	v_pk_mul_f32 v[168:169], v[82:83], v[168:169]
	v_cvt_pk_bf16_f32 v150, v162, v163
	v_cvt_pk_bf16_f32 v151, v164, v165
	v_cvt_pk_bf16_f32 v152, v166, v167
	v_cvt_pk_bf16_f32 v153, v168, v169
	global_store_dwordx4 v[146:147], v[150:153], off
	v_mfma_f32_32x32x16_bf16 v[80:95], v[176:179], v[176:179], 0
	v_mfma_f32_32x32x16_bf16 v[112:127], v[176:179], v[176:179], 0
	s_mov_b32 s9, 0x58000
	v_add_co_u32_e32 v146, vcc, s9, v144
	s_nop 0
	v_addc_co_u32_e32 v147, vcc, 0, v145, vcc
	v_pk_mul_f32 v[162:163], v[108:109], v[170:171] op_sel_hi:[1,0]
	v_pk_mul_f32 v[164:165], v[110:111], v[170:171] op_sel_hi:[1,0]
	v_pk_mul_f32 v[166:167], v[76:77], v[170:171] op_sel_hi:[1,0]
	v_pk_mul_f32 v[168:169], v[78:79], v[170:171] op_sel_hi:[1,0]
	v_exp_f32_e32 v162, v162
	v_exp_f32_e32 v163, v163
	v_exp_f32_e32 v164, v164
	v_exp_f32_e32 v165, v165
	v_exp_f32_e32 v166, v166
	v_exp_f32_e32 v167, v167
	v_exp_f32_e32 v168, v168
	v_exp_f32_e32 v169, v169
	v_pk_add_f32 v[162:163], v[162:163], v[172:173] op_sel_hi:[1,0]
	v_pk_add_f32 v[164:165], v[164:165], v[172:173] op_sel_hi:[1,0]
	v_pk_add_f32 v[166:167], v[166:167], v[172:173] op_sel_hi:[1,0]
	v_pk_add_f32 v[168:169], v[168:169], v[172:173] op_sel_hi:[1,0]
	v_rcp_f32_e32 v162, v162
	v_rcp_f32_e32 v163, v163
	v_rcp_f32_e32 v164, v164
	v_rcp_f32_e32 v165, v165
	v_rcp_f32_e32 v166, v166
	v_rcp_f32_e32 v167, v167
	v_rcp_f32_e32 v168, v168
	v_rcp_f32_e32 v169, v169
	v_pk_mul_f32 v[162:163], v[108:109], v[162:163]
	v_pk_mul_f32 v[164:165], v[110:111], v[164:165]
	v_pk_mul_f32 v[166:167], v[76:77], v[166:167]
	v_pk_mul_f32 v[168:169], v[78:79], v[168:169]
	v_pk_mul_f32 v[162:163], v[104:105], v[162:163]
	v_pk_mul_f32 v[164:165], v[106:107], v[164:165]
	v_pk_mul_f32 v[166:167], v[72:73], v[166:167]
	v_pk_mul_f32 v[168:169], v[74:75], v[168:169]
	v_cvt_pk_bf16_f32 v150, v162, v163
	v_cvt_pk_bf16_f32 v151, v164, v165
	v_cvt_pk_bf16_f32 v152, v166, v167
	v_cvt_pk_bf16_f32 v153, v168, v169
	global_store_dwordx4 v[146:147], v[150:153], off
	s_mov_b32 s9, 0x84000
	v_add_co_u32_e32 v146, vcc, s9, v144
	s_nop 0
	v_addc_co_u32_e32 v147, vcc, 0, v145, vcc
	v_pk_mul_f32 v[162:163], v[100:101], v[170:171] op_sel_hi:[1,0]
	v_pk_mul_f32 v[164:165], v[102:103], v[170:171] op_sel_hi:[1,0]
	v_pk_mul_f32 v[166:167], v[68:69], v[170:171] op_sel_hi:[1,0]
	v_pk_mul_f32 v[168:169], v[70:71], v[170:171] op_sel_hi:[1,0]
	v_exp_f32_e32 v162, v162
	v_exp_f32_e32 v163, v163
	v_exp_f32_e32 v164, v164
	v_exp_f32_e32 v165, v165
	v_exp_f32_e32 v166, v166
	v_exp_f32_e32 v167, v167
	v_exp_f32_e32 v168, v168
	v_exp_f32_e32 v169, v169
	v_pk_add_f32 v[162:163], v[162:163], v[172:173] op_sel_hi:[1,0]
	v_pk_add_f32 v[164:165], v[164:165], v[172:173] op_sel_hi:[1,0]
	v_pk_add_f32 v[166:167], v[166:167], v[172:173] op_sel_hi:[1,0]
	v_pk_add_f32 v[168:169], v[168:169], v[172:173] op_sel_hi:[1,0]
	v_rcp_f32_e32 v162, v162
	v_rcp_f32_e32 v163, v163
	v_rcp_f32_e32 v164, v164
	v_rcp_f32_e32 v165, v165
	v_rcp_f32_e32 v166, v166
	v_rcp_f32_e32 v167, v167
	v_rcp_f32_e32 v168, v168
	v_rcp_f32_e32 v169, v169
	v_pk_mul_f32 v[162:163], v[100:101], v[162:163]
	v_pk_mul_f32 v[164:165], v[102:103], v[164:165]
	v_pk_mul_f32 v[166:167], v[68:69], v[166:167]
	v_pk_mul_f32 v[168:169], v[70:71], v[168:169]
	v_pk_mul_f32 v[162:163], v[96:97], v[162:163]
	v_pk_mul_f32 v[164:165], v[98:99], v[164:165]
	v_pk_mul_f32 v[166:167], v[64:65], v[166:167]
	v_pk_mul_f32 v[168:169], v[66:67], v[168:169]
	v_cvt_pk_bf16_f32 v150, v162, v163
	v_cvt_pk_bf16_f32 v151, v164, v165
	v_cvt_pk_bf16_f32 v152, v166, v167
	v_cvt_pk_bf16_f32 v153, v168, v169
	global_store_dwordx4 v[146:147], v[150:153], off
	v_mfma_f32_32x32x16_bf16 v[64:79], v[176:179], v[176:179], 0
	v_mfma_f32_32x32x16_bf16 v[96:111], v[176:179], v[176:179], 0
	s_mov_b32 s9, 0x160000
	v_add_co_u32_e32 v146, vcc, s9, v144
	s_nop 0
	v_addc_co_u32_e32 v147, vcc, 0, v145, vcc
	v_pk_mul_f32 v[162:163], v[60:61], v[170:171] op_sel_hi:[1,0]
	v_pk_mul_f32 v[164:165], v[62:63], v[170:171] op_sel_hi:[1,0]
	v_pk_mul_f32 v[166:167], v[28:29], v[170:171] op_sel_hi:[1,0]
	v_pk_mul_f32 v[168:169], v[30:31], v[170:171] op_sel_hi:[1,0]
	v_exp_f32_e32 v162, v162
	v_exp_f32_e32 v163, v163
	v_exp_f32_e32 v164, v164
	v_exp_f32_e32 v165, v165
	v_exp_f32_e32 v166, v166
	v_exp_f32_e32 v167, v167
	v_exp_f32_e32 v168, v168
	v_exp_f32_e32 v169, v169
	v_pk_add_f32 v[162:163], v[162:163], v[172:173] op_sel_hi:[1,0]
	v_pk_add_f32 v[164:165], v[164:165], v[172:173] op_sel_hi:[1,0]
	v_pk_add_f32 v[166:167], v[166:167], v[172:173] op_sel_hi:[1,0]
	v_pk_add_f32 v[168:169], v[168:169], v[172:173] op_sel_hi:[1,0]
	v_rcp_f32_e32 v162, v162
	v_rcp_f32_e32 v163, v163
	v_rcp_f32_e32 v164, v164
	v_rcp_f32_e32 v165, v165
	v_rcp_f32_e32 v166, v166
	v_rcp_f32_e32 v167, v167
	v_rcp_f32_e32 v168, v168
	v_rcp_f32_e32 v169, v169
	v_pk_mul_f32 v[162:163], v[60:61], v[162:163]
	v_pk_mul_f32 v[164:165], v[62:63], v[164:165]
	v_pk_mul_f32 v[166:167], v[28:29], v[166:167]
; __device__ __forceinline__ unsigned cvt_pk_bf16(float lo, float hi) { unsigned r; asm volatile("v_cvt_pk_bf16_f32 %0, %1, %2" : "=v"(r) : "v"(lo), "v"(hi)); return r; }
; template <class Epi>
; __device__ __forceinline__ void gemm_phase(LAS unsigned char* lds, const Gemm g, const Sched& S, const Epi& E) {
;     ...
; #pragma unroll
;         for (int a = 0; a < 2; ++a)
; #pragma unroll
;             for (int b = 0; b < 2; ++b)
; #pragma unroll
;                 for (int m = 0; m < 4; ++m)
; #pragma unroll
;                     for (int n = 0; n < 2; ++n) acc[a][b][m][n] = (f32x4){0.f, 0.f, 0.f, 0.f};
;         cur = nxt; cA = nA; cB = nB; ++ui;
;     __device__ __forceinline__ void operator()(AccRef acc, const Unit& u, int wr, int wc, int fr, int fq) const {
;     ...
;         for (int ai = 0; ai < 2; ++ai)
; #pragma unroll
;             for (int m = 0; m < 4; ++m) { const size_t row = (size_t)u.pm * 256 + ai * 128 + wr * 64 + m * 16 + fr; float o[8];
; #pragma unroll
;                 for (int bj = 0; bj < 2; ++bj) { const f32x4 gg = acc[ai][bj][m][0], uu = acc[ai][bj][m][1];
; #pragma unroll
;                     for (int j = 0; j < 4; ++j) o[4 * bj + j] = gg[j] * __builtin_amdgcn_rcpf(1.0f + __expf(-gg[j])) * uu[j]; }
;                 u32x4 w; w.x = cvt_pk_bf16(o[0], o[1]); w.y = cvt_pk_bf16(o[2], o[3]); w.z = cvt_pk_bf16(o[4], o[5]); w.w = cvt_pk_bf16(o[6], o[7]);
;                 *(u32x4*)(act + row * FF_ + (u.pn * 4 + wc) * 32 + 8 * fq) = w; }
	v_pk_mul_f32 v[168:169], v[30:31], v[168:169]
	v_pk_mul_f32 v[162:163], v[56:57], v[162:163]
	v_pk_mul_f32 v[164:165], v[58:59], v[164:165]
	v_pk_mul_f32 v[166:167], v[24:25], v[166:167]
	v_pk_mul_f32 v[168:169], v[26:27], v[168:169]
	v_cvt_pk_bf16_f32 v150, v162, v163
	v_cvt_pk_bf16_f32 v151, v164, v165
	v_cvt_pk_bf16_f32 v152, v166, v167
	v_cvt_pk_bf16_f32 v153, v168, v169
	global_store_dwordx4 v[146:147], v[150:153], off
	s_mov_b32 s9, 0x18c000
	v_add_co_u32_e32 v146, vcc, s9, v144
	s_nop 0
	v_addc_co_u32_e32 v147, vcc, 0, v145, vcc
	v_pk_mul_f32 v[162:163], v[52:53], v[170:171] op_sel_hi:[1,0]
	v_pk_mul_f32 v[164:165], v[54:55], v[170:171] op_sel_hi:[1,0]
	v_pk_mul_f32 v[166:167], v[20:21], v[170:171] op_sel_hi:[1,0]
	v_pk_mul_f32 v[168:169], v[22:23], v[170:171] op_sel_hi:[1,0]
	v_exp_f32_e32 v162, v162
	v_exp_f32_e32 v163, v163
	v_exp_f32_e32 v164, v164
	v_exp_f32_e32 v165, v165
	v_exp_f32_e32 v166, v166
	v_exp_f32_e32 v167, v167
	v_exp_f32_e32 v168, v168
	v_exp_f32_e32 v169, v169
	v_pk_add_f32 v[162:163], v[162:163], v[172:173] op_sel_hi:[1,0]
	v_pk_add_f32 v[164:165], v[164:165], v[172:173] op_sel_hi:[1,0]
	v_pk_add_f32 v[166:167], v[166:167], v[172:173] op_sel_hi:[1,0]
	v_pk_add_f32 v[168:169], v[168:169], v[172:173] op_sel_hi:[1,0]
	v_rcp_f32_e32 v162, v162
	v_rcp_f32_e32 v163, v163
	v_rcp_f32_e32 v164, v164
	v_rcp_f32_e32 v165, v165
	v_rcp_f32_e32 v166, v166
	v_rcp_f32_e32 v167, v167
	v_rcp_f32_e32 v168, v168
	v_rcp_f32_e32 v169, v169
	v_pk_mul_f32 v[162:163], v[52:53], v[162:163]
	v_pk_mul_f32 v[164:165], v[54:55], v[164:165]
	v_pk_mul_f32 v[166:167], v[20:21], v[166:167]
	v_pk_mul_f32 v[168:169], v[22:23], v[168:169]
	v_pk_mul_f32 v[162:163], v[48:49], v[162:163]
	v_pk_mul_f32 v[164:165], v[50:51], v[164:165]
	v_pk_mul_f32 v[166:167], v[16:17], v[166:167]
	v_pk_mul_f32 v[168:169], v[18:19], v[168:169]
	v_cvt_pk_bf16_f32 v150, v162, v163
	v_cvt_pk_bf16_f32 v151, v164, v165
	v_cvt_pk_bf16_f32 v152, v166, v167
	v_cvt_pk_bf16_f32 v153, v168, v169
	global_store_dwordx4 v[146:147], v[150:153], off
	v_mfma_f32_32x32x16_bf16 v[16:31], v[176:179], v[176:179], 0
	v_mfma_f32_32x32x16_bf16 v[48:63], v[176:179], v[176:179], 0
	v_add_co_u32_e32 v146, vcc, s65, v144
	s_nop 0
	v_addc_co_u32_e32 v147, vcc, 0, v145, vcc
	v_pk_mul_f32 v[162:163], v[44:45], v[170:171] op_sel_hi:[1,0]
	v_pk_mul_f32 v[164:165], v[46:47], v[170:171] op_sel_hi:[1,0]
	v_pk_mul_f32 v[166:167], v[12:13], v[170:171] op_sel_hi:[1,0]
	v_pk_mul_f32 v[168:169], v[14:15], v[170:171] op_sel_hi:[1,0]
	v_exp_f32_e32 v162, v162
	v_exp_f32_e32 v163, v163
	v_exp_f32_e32 v164, v164
	v_exp_f32_e32 v165, v165
	v_exp_f32_e32 v166, v166
	v_exp_f32_e32 v167, v167
	v_exp_f32_e32 v168, v168
	v_exp_f32_e32 v169, v169
	v_pk_add_f32 v[162:163], v[162:163], v[172:173] op_sel_hi:[1,0]
	v_pk_add_f32 v[164:165], v[164:165], v[172:173] op_sel_hi:[1,0]
	v_pk_add_f32 v[166:167], v[166:167], v[172:173] op_sel_hi:[1,0]
	v_pk_add_f32 v[168:169], v[168:169], v[172:173] op_sel_hi:[1,0]
	v_rcp_f32_e32 v162, v162
	v_rcp_f32_e32 v163, v163
	v_rcp_f32_e32 v164, v164
	v_rcp_f32_e32 v165, v165
	v_rcp_f32_e32 v166, v166
	v_rcp_f32_e32 v167, v167
	v_rcp_f32_e32 v168, v168
	v_rcp_f32_e32 v169, v169
	v_pk_mul_f32 v[162:163], v[44:45], v[162:163]
	v_pk_mul_f32 v[164:165], v[46:47], v[164:165]
	v_pk_mul_f32 v[166:167], v[12:13], v[166:167]
	v_pk_mul_f32 v[168:169], v[14:15], v[168:169]
	v_pk_mul_f32 v[162:163], v[40:41], v[162:163]
	v_pk_mul_f32 v[164:165], v[42:43], v[164:165]
	v_pk_mul_f32 v[166:167], v[8:9], v[166:167]
	v_pk_mul_f32 v[168:169], v[10:11], v[168:169]
	v_cvt_pk_bf16_f32 v150, v162, v163
	v_cvt_pk_bf16_f32 v151, v164, v165
	v_cvt_pk_bf16_f32 v152, v166, v167
	v_cvt_pk_bf16_f32 v153, v168, v169
	global_store_dwordx4 v[146:147], v[150:153], off
	v_add_co_u32_e32 v144, vcc, 0x1e4000, v144
	v_addc_co_u32_e32 v145, vcc, 0, v145, vcc
	s_andn2_b64 vcc, exec, s[6:7]
	v_pk_mul_f32 v[162:163], v[36:37], v[170:171] op_sel_hi:[1,0]
	v_pk_mul_f32 v[164:165], v[38:39], v[170:171] op_sel_hi:[1,0]
	v_pk_mul_f32 v[166:167], v[4:5], v[170:171] op_sel_hi:[1,0]
	v_pk_mul_f32 v[168:169], v[6:7], v[170:171] op_sel_hi:[1,0]
	v_exp_f32_e32 v162, v162
	v_exp_f32_e32 v163, v163
	v_exp_f32_e32 v164, v164
	v_exp_f32_e32 v165, v165
	v_exp_f32_e32 v166, v166
	v_exp_f32_e32 v167, v167
	v_exp_f32_e32 v168, v168
	v_exp_f32_e32 v169, v169
	v_pk_add_f32 v[162:163], v[162:163], v[172:173] op_sel_hi:[1,0]
	v_pk_add_f32 v[164:165], v[164:165], v[172:173] op_sel_hi:[1,0]
	v_pk_add_f32 v[166:167], v[166:167], v[172:173] op_sel_hi:[1,0]
	v_pk_add_f32 v[168:169], v[168:169], v[172:173] op_sel_hi:[1,0]
	v_rcp_f32_e32 v162, v162
	v_rcp_f32_e32 v163, v163
	v_rcp_f32_e32 v164, v164
	v_rcp_f32_e32 v165, v165
	v_rcp_f32_e32 v166, v166
	v_rcp_f32_e32 v167, v167
	v_rcp_f32_e32 v168, v168
	v_rcp_f32_e32 v169, v169
	v_pk_mul_f32 v[162:163], v[36:37], v[162:163]
	v_pk_mul_f32 v[164:165], v[38:39], v[164:165]
	v_pk_mul_f32 v[166:167], v[4:5], v[166:167]
	v_pk_mul_f32 v[168:169], v[6:7], v[168:169]
	v_pk_mul_f32 v[162:163], v[32:33], v[162:163]
	v_pk_mul_f32 v[164:165], v[34:35], v[164:165]
	v_pk_mul_f32 v[166:167], v[0:1], v[166:167]
	v_pk_mul_f32 v[168:169], v[2:3], v[168:169]
	v_cvt_pk_bf16_f32 v150, v162, v163
	v_cvt_pk_bf16_f32 v151, v164, v165
	v_cvt_pk_bf16_f32 v152, v166, v167
	v_cvt_pk_bf16_f32 v153, v168, v169
	global_store_dwordx4 v[144:145], v[150:153], off
	v_mfma_f32_32x32x16_bf16 v[0:15], v[176:179], v[176:179], 0
	v_mfma_f32_32x32x16_bf16 v[32:47], v[176:179], v[176:179], 0
	s_cbranch_vccz .LBB0_173
	s_mov_b64 s[20:21], s[24:25]
	s_andn2_b64 vcc, exec, s[4:5]
	s_mov_b64 s[24:25], s[20:21]
	s_cbranch_vccnz .LBB0_174

; template <class Epi>
; __device__ __forceinline__ void gemm_phase(LAS unsigned char* lds, const Gemm g, const Sched& S, const Epi& E) {
;     ...
; #pragma unroll
;         for (int a = 0; a < 2; ++a)
; #pragma unroll
;             for (int b = 0; b < 2; ++b)
; #pragma unroll
;                 for (int m = 0; m < 4; ++m)
; #pragma unroll
;                     for (int n = 0; n < 2; ++n) acc[a][b][m][n] = (f32x4){0.f, 0.f, 0.f, 0.f};
;         cur = nxt; cA = nA; cB = nB; ++ui;
.LBB0_2084:
	s_mov_b32 s58, s18
	s_mov_b32 s12, s20
	s_mov_b64 s[14:15], s[24:25]
	s_mov_b32 s57, s50
	s_andn2_b64 vcc, exec, s[8:9]
	s_mov_b64 s[36:37], s[22:23]
	s_cbranch_vccz .LBB0_2091

; #define PG8_STAGE(bufoff, gbase, voff) do { _Pragma("unroll") for (int _i = 0; _i < 2; ++_i) \
;         __builtin_amdgcn_global_load_lds((const unsigned*)((const char*)(gbase) + (voff)[_i]), (LAS unsigned*)(lds + (bufoff) + ldsw + _i * 8192), 16, 0, 0); } while (0)
; #define PG8_LDA(dst, b, h) do { _Pragma("unroll") for (int m = 0; m < 4; ++m) _Pragma("unroll") for (int k = 0; k < 2; ++k) dst[m][k] = *(const LAS bf16x8*)(lds + PG8_SA(b, h) + aoff + m * 2048 + k * 1024); } while (0)
; #define PG8_LDB(dst, b, h) do { _Pragma("unroll") for (int n = 0; n < 2; ++n) _Pragma("unroll") for (int k = 0; k < 2; ++k) dst[n][k] = *(const LAS bf16x8*)(lds + PG8_SB(b, h) + boff + n * 2048 + k * 1024); } while (0)
; #define PG8_MMA(ai, bj, At, Bt) do { __builtin_amdgcn_s_setprio(1); _Pragma("unroll") for (int m = 0; m < 4; ++m) _Pragma("unroll") for (int n = 0; n < 2; ++n) _Pragma("unroll") for (int k = 0; k < 2; ++k) \
;         acc[ai][bj][m][n] = __builtin_amdgcn_mfma_f32_16x16x32_bf16(Bt[n][k], At[m][k], acc[ai][bj][m][n], 0, 0, 0); __builtin_amdgcn_s_setprio(0); } while (0)
; #define PG8_WAIT_L(n) asm volatile("s_waitcnt lgkmcnt(" #n ")" ::: "memory")
; #define PG8_BAR __builtin_amdgcn_s_barrier()
; #define PG8_SCHED __builtin_amdgcn_sched_barrier(0)
; template <class Epi>
; __device__ __forceinline__ void gemm_phase(LAS unsigned char* lds, const Gemm g, const Sched& S, const Epi& E) {
;     ...
;             PG8_LDB(B0, 0, 0); PG8_SCHED; PG8_LDA(At, 0, 0); PG8_STAGE(PG8_SA(1, 1), a1 + hstepA, voffA);
;             PG8_WAIT_L(8); PG8_BAR; PG8_WAIT_L(0); PG8_MMA(0, 0, At, B0); PG8_BAR; PG8_SCHED;
;             PG8_LDB(B1, 0, 1); PG8_STAGE(PG8_SB(0, 0), b2, voffB);
;             PG8_BAR; PG8_WAIT_L(0); PG8_MMA(0, 1, At, B1); PG8_BAR;
;             PG8_LDA(At, 0, 1); PG8_STAGE(PG8_SA(0, 0), a2, voffA);
;             PG8_BAR; PG8_WAIT_L(0); PG8_MMA(1, 0, At, B0); PG8_BAR; PG8_SCHED;
.LBB0_2088:
	v_add_u32_e32 v162, s62, v148
	s_add_u32 s38, s14, s36
	ds_read_b128 v[150:153], v162
	ds_read_b128 v[154:157], v162 offset:1024
	ds_read_b128 v[158:161], v162 offset:2048
	ds_read_b128 v[162:165], v162 offset:3072
	s_addc_u32 s39, s15, s37
	s_add_u32 s38, s38, 0x100
	s_addc_u32 s39, s39, 0
	s_add_u32 s82, s13, s36
	s_addc_u32 s83, s51, s37
	s_cmpk_eq_i32 s36, 0xf00
	s_cselect_b32 s55, s21, s39
	s_cselect_b32 s54, s79, s38
	s_cselect_b32 s39, s19, s83
	s_cselect_b32 s38, s80, s82
	v_lshl_add_u64 v[190:191], v[144:145], 0, s[36:37]
	s_add_i32 m0, s43, 0xc000
	ds_read_b128 v[166:169], v149
	ds_read_b128 v[170:173], v149 offset:1024
	ds_read_b128 v[174:177], v149 offset:2048
	ds_read_b128 v[178:181], v149 offset:3072
	ds_read_b128 v[182:185], v149 offset:4096
	ds_read_b128 v[186:189], v149 offset:5120
	ds_read_b128 v[194:197], v149 offset:6144
	ds_read_b128 v[198:201], v149 offset:7168
	global_load_lds_dwordx4 v[190:191], off
	v_lshl_add_u64 v[190:191], v[146:147], 0, s[36:37]
	s_add_i32 m0, s43, 0xe000
	s_nop 0
	global_load_lds_dwordx4 v[190:191], off
	s_waitcnt lgkmcnt(8)
	s_barrier
	s_waitcnt lgkmcnt(0)
	s_setprio 1
	s_waitcnt lgkmcnt(0)
	v_mfma_f32_16x16x32_bf16 v[124:127], v[150:153], v[166:169], v[124:127]
	v_mfma_f32_16x16x32_bf16 v[120:123], v[158:161], v[166:169], v[120:123]
	v_mfma_f32_16x16x32_bf16 v[116:119], v[150:153], v[174:177], v[116:119]
	v_mfma_f32_16x16x32_bf16 v[112:115], v[158:161], v[174:177], v[112:115]
	v_mfma_f32_16x16x32_bf16 v[108:111], v[150:153], v[182:185], v[108:111]
	v_mfma_f32_16x16x32_bf16 v[104:107], v[158:161], v[182:185], v[104:107]
	v_mfma_f32_16x16x32_bf16 v[100:103], v[150:153], v[194:197], v[100:103]
	v_mfma_f32_16x16x32_bf16 v[96:99], v[158:161], v[194:197], v[96:99]
	v_mfma_f32_16x16x32_bf16 v[124:127], v[154:157], v[170:173], v[124:127]
	v_mfma_f32_16x16x32_bf16 v[120:123], v[162:165], v[170:173], v[120:123]
	v_mfma_f32_16x16x32_bf16 v[116:119], v[154:157], v[178:181], v[116:119]
	v_mfma_f32_16x16x32_bf16 v[112:115], v[162:165], v[178:181], v[112:115]
	v_mfma_f32_16x16x32_bf16 v[108:111], v[154:157], v[186:189], v[108:111]
	v_mfma_f32_16x16x32_bf16 v[104:107], v[162:165], v[186:189], v[104:107]
	v_mfma_f32_16x16x32_bf16 v[100:103], v[154:157], v[198:201], v[100:103]
	v_mfma_f32_16x16x32_bf16 v[96:99], v[162:165], v[198:201], v[96:99]
	s_setprio 0
	s_barrier
	v_add_u32_e32 v190, s63, v148
	s_add_i32 s82, s62, s34
	ds_read_b128 v[202:205], v190
	ds_read_b128 v[206:209], v190 offset:1024
	ds_read_b128 v[210:213], v190 offset:2048
	ds_read_b128 v[214:217], v190 offset:3072
	v_lshl_add_u64 v[190:191], s[38:39], 0, v[130:131]
	s_mov_b32 m0, s82
	v_lshl_add_u64 v[218:219], s[38:39], 0, v[128:129]
	global_load_lds_dwordx4 v[190:191], off
	s_add_i32 m0, s82, 0x2000
	s_nop 0
	global_load_lds_dwordx4 v[218:219], off
	s_barrier
	s_waitcnt lgkmcnt(0)
	s_setprio 1
	s_waitcnt lgkmcnt(0)
	v_mfma_f32_16x16x32_bf16 v[92:95], v[202:205], v[166:169], v[92:95]
	v_mfma_f32_16x16x32_bf16 v[88:91], v[210:213], v[166:169], v[88:91]
	v_mfma_f32_16x16x32_bf16 v[84:87], v[202:205], v[174:177], v[84:87]
	v_mfma_f32_16x16x32_bf16 v[80:83], v[210:213], v[174:177], v[80:83]
	v_mfma_f32_16x16x32_bf16 v[76:79], v[202:205], v[182:185], v[76:79]
	v_mfma_f32_16x16x32_bf16 v[72:75], v[210:213], v[182:185], v[72:75]
	v_mfma_f32_16x16x32_bf16 v[68:71], v[202:205], v[194:197], v[68:71]
	v_mfma_f32_16x16x32_bf16 v[64:67], v[210:213], v[194:197], v[64:67]
	v_mfma_f32_16x16x32_bf16 v[92:95], v[206:209], v[170:173], v[92:95]
	v_mfma_f32_16x16x32_bf16 v[88:91], v[214:217], v[170:173], v[88:91]
	v_mfma_f32_16x16x32_bf16 v[84:87], v[206:209], v[178:181], v[84:87]
	v_mfma_f32_16x16x32_bf16 v[80:83], v[214:217], v[178:181], v[80:83]
	v_mfma_f32_16x16x32_bf16 v[76:79], v[206:209], v[186:189], v[76:79]
	v_mfma_f32_16x16x32_bf16 v[72:75], v[214:217], v[186:189], v[72:75]
	v_mfma_f32_16x16x32_bf16 v[68:71], v[206:209], v[198:201], v[68:71]
	v_mfma_f32_16x16x32_bf16 v[64:67], v[214:217], v[198:201], v[64:67]
	s_setprio 0
	s_mov_b32 m0, s43
	v_lshl_add_u64 v[220:221], s[54:55], 0, v[130:131]
	s_barrier
	ds_read_b128 v[166:169], v149 offset:16384
	ds_read_b128 v[170:173], v149 offset:17408
	ds_read_b128 v[174:177], v149 offset:18432
	ds_read_b128 v[178:181], v149 offset:19456
	ds_read_b128 v[182:185], v149 offset:20480
	ds_read_b128 v[186:189], v149 offset:21504
	ds_read_b128 v[194:197], v149 offset:22528
	ds_read_b128 v[198:201], v149 offset:23552
	global_load_lds_dwordx4 v[220:221], off
	v_lshl_add_u64 v[222:223], s[54:55], 0, v[128:129]
	s_mov_b32 m0, s52
	s_nop 0
	global_load_lds_dwordx4 v[222:223], off
	s_barrier
	s_waitcnt lgkmcnt(0)
	s_setprio 1
	s_waitcnt lgkmcnt(0)
	v_mfma_f32_16x16x32_bf16 v[60:63], v[150:153], v[166:169], v[60:63]
	v_mfma_f32_16x16x32_bf16 v[56:59], v[158:161], v[166:169], v[56:59]
	v_mfma_f32_16x16x32_bf16 v[52:55], v[150:153], v[174:177], v[52:55]
	v_mfma_f32_16x16x32_bf16 v[48:51], v[158:161], v[174:177], v[48:51]
	v_mfma_f32_16x16x32_bf16 v[44:47], v[150:153], v[182:185], v[44:47]
	v_mfma_f32_16x16x32_bf16 v[40:43], v[158:161], v[182:185], v[40:43]
	v_mfma_f32_16x16x32_bf16 v[36:39], v[150:153], v[194:197], v[36:39]
	v_mfma_f32_16x16x32_bf16 v[32:35], v[158:161], v[194:197], v[32:35]
	v_mfma_f32_16x16x32_bf16 v[60:63], v[154:157], v[170:173], v[60:63]
	v_mfma_f32_16x16x32_bf16 v[56:59], v[162:165], v[170:173], v[56:59]
	v_mfma_f32_16x16x32_bf16 v[52:55], v[154:157], v[178:181], v[52:55]
	v_mfma_f32_16x16x32_bf16 v[48:51], v[162:165], v[178:181], v[48:51]
	v_mfma_f32_16x16x32_bf16 v[44:47], v[154:157], v[186:189], v[44:47]
	v_mfma_f32_16x16x32_bf16 v[40:43], v[162:165], v[186:189], v[40:43]
	v_mfma_f32_16x16x32_bf16 v[36:39], v[154:157], v[198:201], v[36:39]
	v_mfma_f32_16x16x32_bf16 v[32:35], v[162:165], v[198:201], v[32:35]
	s_setprio 0
	s_barrier
; #define PG8_STAGE(bufoff, gbase, voff) do { _Pragma("unroll") for (int _i = 0; _i < 2; ++_i) \
;         __builtin_amdgcn_global_load_lds((const unsigned*)((const char*)(gbase) + (voff)[_i]), (LAS unsigned*)(lds + (bufoff) + ldsw + _i * 8192), 16, 0, 0); } while (0)
; #define PG8_LDA(dst, b, h) do { _Pragma("unroll") for (int m = 0; m < 4; ++m) _Pragma("unroll") for (int k = 0; k < 2; ++k) dst[m][k] = *(const LAS bf16x8*)(lds + PG8_SA(b, h) + aoff + m * 2048 + k * 1024); } while (0)
; #define PG8_LDB(dst, b, h) do { _Pragma("unroll") for (int n = 0; n < 2; ++n) _Pragma("unroll") for (int k = 0; k < 2; ++k) dst[n][k] = *(const LAS bf16x8*)(lds + PG8_SB(b, h) + boff + n * 2048 + k * 1024); } while (0)
; #define PG8_MMA(ai, bj, At, Bt) do { __builtin_amdgcn_s_setprio(1); _Pragma("unroll") for (int m = 0; m < 4; ++m) _Pragma("unroll") for (int n = 0; n < 2; ++n) _Pragma("unroll") for (int k = 0; k < 2; ++k) \
;         acc[ai][bj][m][n] = __builtin_amdgcn_mfma_f32_16x16x32_bf16(Bt[n][k], At[m][k], acc[ai][bj][m][n], 0, 0, 0); __builtin_amdgcn_s_setprio(0); } while (0)
; #define PG8_WAIT_V(n) asm volatile("s_waitcnt vmcnt(" #n ")" ::: "memory")
; #define PG8_WAIT_L(n) asm volatile("s_waitcnt lgkmcnt(" #n ")" ::: "memory")
; #define PG8_BAR __builtin_amdgcn_s_barrier()
; #define PG8_SCHED __builtin_amdgcn_sched_barrier(0)
; template <class Epi>
; __device__ __forceinline__ void gemm_phase(LAS unsigned char* lds, const Gemm g, const Sched& S, const Epi& E) {
;     ...
;             PG8_STAGE(PG8_SB(0, 1), b2 + hstepB, voffB);
;             PG8_WAIT_V(6); PG8_BAR; PG8_MMA(1, 1, At, B1); PG8_BAR;
;             PG8_LDB(B0, 1, 0); PG8_SCHED; PG8_LDA(At, 1, 0); PG8_STAGE(PG8_SA(0, 1), a2 + hstepA, voffA);
;             PG8_WAIT_L(8); PG8_BAR; PG8_WAIT_L(0); PG8_MMA(0, 0, At, B0); PG8_BAR; PG8_SCHED;
;             PG8_LDB(B1, 1, 1); PG8_STAGE(PG8_SB(1, 0), b3, voffB);
;             PG8_BAR; PG8_WAIT_L(0); PG8_MMA(0, 1, At, B1); PG8_BAR;
;             PG8_LDA(At, 1, 1); PG8_STAGE(PG8_SA(1, 0), a3, voffA);
;             PG8_BAR; PG8_WAIT_L(0); PG8_MMA(1, 0, At, B0); PG8_BAR; PG8_SCHED;
	s_add_u32 s82, s38, 0x80000
	s_addc_u32 s83, s39, 0
	s_add_i32 s84, s63, s34
	v_lshl_add_u64 v[150:151], s[82:83], 0, v[130:131]
	s_mov_b32 m0, s84
	s_nop 0
	global_load_lds_dwordx4 v[150:151], off
	v_lshl_add_u64 v[150:151], s[82:83], 0, v[128:129]
	s_add_i32 m0, s84, 0x2000
	s_nop 0
	global_load_lds_dwordx4 v[150:151], off
	s_waitcnt vmcnt(6)
	s_barrier
	s_setprio 1
	v_mfma_f32_16x16x32_bf16 v[28:31], v[202:205], v[166:169], v[28:31]
	v_mfma_f32_16x16x32_bf16 v[24:27], v[210:213], v[166:169], v[24:27]
	v_mfma_f32_16x16x32_bf16 v[20:23], v[202:205], v[174:177], v[20:23]
	v_mfma_f32_16x16x32_bf16 v[16:19], v[210:213], v[174:177], v[16:19]
	v_mfma_f32_16x16x32_bf16 v[12:15], v[202:205], v[182:185], v[12:15]
	v_mfma_f32_16x16x32_bf16 v[8:11], v[210:213], v[182:185], v[8:11]
	v_mfma_f32_16x16x32_bf16 v[4:7], v[202:205], v[194:197], v[4:7]
	v_mfma_f32_16x16x32_bf16 v[0:3], v[210:213], v[194:197], v[0:3]
	v_mfma_f32_16x16x32_bf16 v[28:31], v[206:209], v[170:173], v[28:31]
	v_mfma_f32_16x16x32_bf16 v[24:27], v[214:217], v[170:173], v[24:27]
	v_mfma_f32_16x16x32_bf16 v[20:23], v[206:209], v[178:181], v[20:23]
	v_mfma_f32_16x16x32_bf16 v[16:19], v[214:217], v[178:181], v[16:19]
	v_mfma_f32_16x16x32_bf16 v[12:15], v[206:209], v[186:189], v[12:15]
	v_mfma_f32_16x16x32_bf16 v[8:11], v[214:217], v[186:189], v[8:11]
	v_mfma_f32_16x16x32_bf16 v[4:7], v[206:209], v[198:201], v[4:7]
	v_mfma_f32_16x16x32_bf16 v[0:3], v[214:217], v[198:201], v[0:3]
	s_setprio 0
	s_add_i32 s82, 0, 0x18000
	v_add_u32_e32 v162, s82, v148
	s_barrier
	ds_read_b128 v[150:153], v162
	ds_read_b128 v[154:157], v162 offset:1024
	ds_read_b128 v[158:161], v162 offset:2048
	ds_read_b128 v[162:165], v162 offset:3072
	s_add_u32 s54, s54, 0x80000
	s_addc_u32 s55, s55, 0
	s_mov_b32 m0, s53
	v_lshl_add_u64 v[202:203], s[54:55], 0, v[130:131]
	ds_read_b128 v[166:169], v149 offset:32768
	ds_read_b128 v[170:173], v149 offset:33792
	ds_read_b128 v[174:177], v149 offset:34816
	ds_read_b128 v[178:181], v149 offset:35840
	ds_read_b128 v[182:185], v149 offset:36864
	ds_read_b128 v[186:189], v149 offset:37888
	ds_read_b128 v[194:197], v149 offset:38912
	ds_read_b128 v[198:201], v149 offset:39936
	global_load_lds_dwordx4 v[202:203], off
	v_lshl_add_u64 v[202:203], s[54:55], 0, v[128:129]
	s_mov_b32 m0, s56
	s_nop 0
	global_load_lds_dwordx4 v[202:203], off
	s_waitcnt lgkmcnt(8)
	s_barrier
	s_waitcnt lgkmcnt(0)
	s_setprio 1
	s_waitcnt lgkmcnt(0)
	v_mfma_f32_16x16x32_bf16 v[124:127], v[150:153], v[166:169], v[124:127]
	v_mfma_f32_16x16x32_bf16 v[120:123], v[158:161], v[166:169], v[120:123]
	v_mfma_f32_16x16x32_bf16 v[116:119], v[150:153], v[174:177], v[116:119]
	v_mfma_f32_16x16x32_bf16 v[112:115], v[158:161], v[174:177], v[112:115]
	v_mfma_f32_16x16x32_bf16 v[108:111], v[150:153], v[182:185], v[108:111]
	v_mfma_f32_16x16x32_bf16 v[104:107], v[158:161], v[182:185], v[104:107]
	v_mfma_f32_16x16x32_bf16 v[100:103], v[150:153], v[194:197], v[100:103]
	v_mfma_f32_16x16x32_bf16 v[96:99], v[158:161], v[194:197], v[96:99]
	v_mfma_f32_16x16x32_bf16 v[124:127], v[154:157], v[170:173], v[124:127]
	v_mfma_f32_16x16x32_bf16 v[120:123], v[162:165], v[170:173], v[120:123]
	v_mfma_f32_16x16x32_bf16 v[116:119], v[154:157], v[178:181], v[116:119]
	v_mfma_f32_16x16x32_bf16 v[112:115], v[162:165], v[178:181], v[112:115]
	v_mfma_f32_16x16x32_bf16 v[108:111], v[154:157], v[186:189], v[108:111]
	v_mfma_f32_16x16x32_bf16 v[104:107], v[162:165], v[186:189], v[104:107]
	v_mfma_f32_16x16x32_bf16 v[100:103], v[154:157], v[198:201], v[100:103]
	v_mfma_f32_16x16x32_bf16 v[96:99], v[162:165], v[198:201], v[96:99]
	s_setprio 0
	s_barrier
	s_add_i32 s54, 0, 0x1c000
	s_add_i32 s55, s82, s34
	v_add_u32_e32 v214, s54, v148
	v_lshl_add_u64 v[190:191], v[190:191], 0, s[16:17]
	s_mov_b32 m0, s55
	ds_read_b128 v[202:205], v214
	ds_read_b128 v[206:209], v214 offset:1024
	ds_read_b128 v[210:213], v214 offset:2048
	ds_read_b128 v[214:217], v214 offset:3072
	global_load_lds_dwordx4 v[190:191], off
	v_lshl_add_u64 v[190:191], v[218:219], 0, s[16:17]
	s_add_i32 m0, s55, 0x2000
	s_nop 0
	global_load_lds_dwordx4 v[190:191], off
	s_barrier
	s_waitcnt lgkmcnt(0)
	s_setprio 1
	s_waitcnt lgkmcnt(0)
	v_mfma_f32_16x16x32_bf16 v[92:95], v[202:205], v[166:169], v[92:95]
	v_mfma_f32_16x16x32_bf16 v[88:91], v[210:213], v[166:169], v[88:91]
	v_mfma_f32_16x16x32_bf16 v[84:87], v[202:205], v[174:177], v[84:87]
	v_mfma_f32_16x16x32_bf16 v[80:83], v[210:213], v[174:177], v[80:83]
	v_mfma_f32_16x16x32_bf16 v[76:79], v[202:205], v[182:185], v[76:79]
	v_mfma_f32_16x16x32_bf16 v[72:75], v[210:213], v[182:185], v[72:75]
	v_mfma_f32_16x16x32_bf16 v[68:71], v[202:205], v[194:197], v[68:71]
	v_mfma_f32_16x16x32_bf16 v[64:67], v[210:213], v[194:197], v[64:67]
	v_mfma_f32_16x16x32_bf16 v[92:95], v[206:209], v[170:173], v[92:95]
	v_mfma_f32_16x16x32_bf16 v[88:91], v[214:217], v[170:173], v[88:91]
	v_mfma_f32_16x16x32_bf16 v[84:87], v[206:209], v[178:181], v[84:87]
	v_mfma_f32_16x16x32_bf16 v[80:83], v[214:217], v[178:181], v[80:83]
	v_mfma_f32_16x16x32_bf16 v[76:79], v[206:209], v[186:189], v[76:79]
	v_mfma_f32_16x16x32_bf16 v[72:75], v[214:217], v[186:189], v[72:75]
	v_mfma_f32_16x16x32_bf16 v[68:71], v[206:209], v[198:201], v[68:71]
	v_mfma_f32_16x16x32_bf16 v[64:67], v[214:217], v[198:201], v[64:67]
	s_setprio 0
	s_mov_b32 m0, s60
	v_lshl_add_u64 v[190:191], v[220:221], 0, s[16:17]
	s_barrier
	ds_read_b128 v[166:169], v149 offset:49152
	ds_read_b128 v[170:173], v149 offset:50176
	ds_read_b128 v[174:177], v149 offset:51200
	ds_read_b128 v[178:181], v149 offset:52224
	ds_read_b128 v[182:185], v149 offset:53248
	ds_read_b128 v[186:189], v149 offset:54272
	ds_read_b128 v[194:197], v149 offset:55296
	ds_read_b128 v[198:201], v149 offset:56320
	global_load_lds_dwordx4 v[190:191], off
	v_lshl_add_u64 v[190:191], v[222:223], 0, s[16:17]
	s_mov_b32 m0, s61
	s_nop 0
	global_load_lds_dwordx4 v[190:191], off
	s_barrier
; __device__ __forceinline__ unsigned cvt_pk_bf16(float lo, float hi) { unsigned r; asm volatile("v_cvt_pk_bf16_f32 %0, %1, %2" : "=v"(r) : "v"(lo), "v"(hi)); return r; }
; #define PG8_STAGE(bufoff, gbase, voff) do { _Pragma("unroll") for (int _i = 0; _i < 2; ++_i) \
;         __builtin_amdgcn_global_load_lds((const unsigned*)((const char*)(gbase) + (voff)[_i]), (LAS unsigned*)(lds + (bufoff) + ldsw + _i * 8192), 16, 0, 0); } while (0)
; #define PG8_MMA(ai, bj, At, Bt) do { __builtin_amdgcn_s_setprio(1); _Pragma("unroll") for (int m = 0; m < 4; ++m) _Pragma("unroll") for (int n = 0; n < 2; ++n) _Pragma("unroll") for (int k = 0; k < 2; ++k) \
;         acc[ai][bj][m][n] = __builtin_amdgcn_mfma_f32_16x16x32_bf16(Bt[n][k], At[m][k], acc[ai][bj][m][n], 0, 0, 0); __builtin_amdgcn_s_setprio(0); } while (0)
; #define PG8_WAIT_V(n) asm volatile("s_waitcnt vmcnt(" #n ")" ::: "memory")
; #define PG8_WAIT_L(n) asm volatile("s_waitcnt lgkmcnt(" #n ")" ::: "memory")
; #define PG8_BAR __builtin_amdgcn_s_barrier()
; #define PG8_SCHED __builtin_amdgcn_sched_barrier(0)
; template <class Epi>
; __device__ __forceinline__ void gemm_phase(LAS unsigned char* lds, const Gemm g, const Sched& S, const Epi& E) {
;     ...
;             PG8_BAR; PG8_WAIT_L(0); PG8_MMA(1, 0, At, B0); PG8_BAR; PG8_SCHED;
;             PG8_STAGE(PG8_SB(1, 1), b3 + hstepB, voffB);
;             PG8_WAIT_V(6); PG8_BAR; PG8_MMA(1, 1, At, B1); PG8_BAR;
;     __device__ __forceinline__ void operator()(AccRef acc, const Unit& u, int wr, int wc, int fr, int fq) const {
;     ...
;             for (int m = 0; m < 4; ++m) { const size_t row = (size_t)u.pm * 256 + ai * 128 + wr * 64 + m * 16 + fr; float o[8];
; #pragma unroll
;                 for (int bj = 0; bj < 2; ++bj) { const f32x4 gg = acc[ai][bj][m][0], uu = acc[ai][bj][m][1];
; #pragma unroll
;                     for (int j = 0; j < 4; ++j) o[4 * bj + j] = gg[j] * __builtin_amdgcn_rcpf(1.0f + __expf(-gg[j])) * uu[j]; }
;                 u32x4 w; w.x = cvt_pk_bf16(o[0], o[1]); w.y = cvt_pk_bf16(o[2], o[3]); w.z = cvt_pk_bf16(o[4], o[5]); w.w = cvt_pk_bf16(o[6], o[7]);
;                 *(u32x4*)(act + row * FF_ + (u.pn * 4 + wc) * 32 + 8 * fq) = w; }
	s_waitcnt lgkmcnt(0)
	s_setprio 1
	s_waitcnt lgkmcnt(0)
	v_mfma_f32_16x16x32_bf16 v[60:63], v[150:153], v[166:169], v[60:63]
	v_mfma_f32_16x16x32_bf16 v[56:59], v[158:161], v[166:169], v[56:59]
	v_mfma_f32_16x16x32_bf16 v[52:55], v[150:153], v[174:177], v[52:55]
	v_mfma_f32_16x16x32_bf16 v[48:51], v[158:161], v[174:177], v[48:51]
	v_mfma_f32_16x16x32_bf16 v[44:47], v[150:153], v[182:185], v[44:47]
	v_mfma_f32_16x16x32_bf16 v[40:43], v[158:161], v[182:185], v[40:43]
	v_mfma_f32_16x16x32_bf16 v[36:39], v[150:153], v[194:197], v[36:39]
	v_mfma_f32_16x16x32_bf16 v[32:35], v[158:161], v[194:197], v[32:35]
	v_mfma_f32_16x16x32_bf16 v[60:63], v[154:157], v[170:173], v[60:63]
	v_mfma_f32_16x16x32_bf16 v[56:59], v[162:165], v[170:173], v[56:59]
	v_mfma_f32_16x16x32_bf16 v[52:55], v[154:157], v[178:181], v[52:55]
	v_mfma_f32_16x16x32_bf16 v[48:51], v[162:165], v[178:181], v[48:51]
	v_mfma_f32_16x16x32_bf16 v[44:47], v[154:157], v[186:189], v[44:47]
	v_mfma_f32_16x16x32_bf16 v[40:43], v[162:165], v[186:189], v[40:43]
	v_mfma_f32_16x16x32_bf16 v[36:39], v[154:157], v[198:201], v[36:39]
	v_mfma_f32_16x16x32_bf16 v[32:35], v[162:165], v[198:201], v[32:35]
	s_setprio 0
	s_barrier
	s_add_u32 s38, s38, 0x80080
	s_addc_u32 s39, s39, 0
	s_add_i32 s54, s54, s34
	v_lshl_add_u64 v[150:151], s[38:39], 0, v[130:131]
	s_mov_b32 m0, s54
	s_nop 0
	global_load_lds_dwordx4 v[150:151], off
	v_lshl_add_u64 v[150:151], s[38:39], 0, v[128:129]
	s_add_i32 m0, s54, 0x2000
	s_nop 0
	global_load_lds_dwordx4 v[150:151], off
	s_waitcnt vmcnt(6)
	s_barrier
	s_setprio 1
	v_mfma_f32_16x16x32_bf16 v[28:31], v[202:205], v[166:169], v[28:31]
	v_mfma_f32_16x16x32_bf16 v[24:27], v[210:213], v[166:169], v[24:27]
	v_mfma_f32_16x16x32_bf16 v[20:23], v[202:205], v[174:177], v[20:23]
	v_mfma_f32_16x16x32_bf16 v[16:19], v[210:213], v[174:177], v[16:19]
	v_mfma_f32_16x16x32_bf16 v[12:15], v[202:205], v[182:185], v[12:15]
	v_mfma_f32_16x16x32_bf16 v[8:11], v[210:213], v[182:185], v[8:11]
	v_mfma_f32_16x16x32_bf16 v[4:7], v[202:205], v[194:197], v[4:7]
	v_mfma_f32_16x16x32_bf16 v[0:3], v[210:213], v[194:197], v[0:3]
	v_mfma_f32_16x16x32_bf16 v[28:31], v[206:209], v[170:173], v[28:31]
	v_mfma_f32_16x16x32_bf16 v[24:27], v[214:217], v[170:173], v[24:27]
	v_mfma_f32_16x16x32_bf16 v[20:23], v[206:209], v[178:181], v[20:23]
	v_mfma_f32_16x16x32_bf16 v[16:19], v[214:217], v[178:181], v[16:19]
	v_mfma_f32_16x16x32_bf16 v[12:15], v[206:209], v[186:189], v[12:15]
	v_mfma_f32_16x16x32_bf16 v[8:11], v[214:217], v[186:189], v[8:11]
	v_mfma_f32_16x16x32_bf16 v[4:7], v[206:209], v[198:201], v[4:7]
	v_mfma_f32_16x16x32_bf16 v[0:3], v[214:217], v[198:201], v[0:3]
	s_setprio 0
	s_add_i32 s81, s81, 2
	s_add_u32 s36, s36, 0x100
	s_addc_u32 s37, s37, 0
	s_cmp_gt_u32 s81, 29
	s_barrier
	s_cbranch_scc0 .LBB0_2088
	v_mov_b32_e32 v170, 0xbfb8aa3b
	v_mov_b32_e32 v172, 1.0
	v_mov_b64_e32 v[176:177], 0
	v_mov_b64_e32 v[178:179], 0
	s_add_u32 s36, s13, 0xffffff00
	s_addc_u32 s37, s51, -1
	s_ashr_i32 s13, s12, 31
	s_lshl_b64 s[38:39], s[12:13], 8
	v_lshl_add_u64 v[144:145], v[134:135], 0, s[38:39]
	v_mov_b64_e32 v[146:147], s[44:45]
	v_mad_u64_u32 v[146:147], s[54:55], v144, s64, v[146:147]
	s_lshl_b32 s13, s58, 7
	v_mov_b32_e32 v144, v147
	s_or_b32 s38, s13, s59
	v_mad_u64_u32 v[144:145], s[54:55], v145, s64, v[144:145]
	s_ashr_i32 s39, s38, 31
	v_mov_b32_e32 v147, v144
	v_lshl_add_u64 v[144:145], s[38:39], 1, v[146:147]
	v_lshl_add_u64 v[144:145], v[144:145], 0, v[132:133]
	v_pk_mul_f32 v[162:163], v[124:125], v[170:171] op_sel_hi:[1,0]
	v_pk_mul_f32 v[164:165], v[126:127], v[170:171] op_sel_hi:[1,0]
	v_pk_mul_f32 v[166:167], v[92:93], v[170:171] op_sel_hi:[1,0]
	v_pk_mul_f32 v[168:169], v[94:95], v[170:171] op_sel_hi:[1,0]
	v_exp_f32_e32 v162, v162
	v_exp_f32_e32 v163, v163
	v_exp_f32_e32 v164, v164
	v_exp_f32_e32 v165, v165
	v_exp_f32_e32 v166, v166
	v_exp_f32_e32 v167, v167
	v_exp_f32_e32 v168, v168
	v_exp_f32_e32 v169, v169
	v_pk_add_f32 v[162:163], v[162:163], v[172:173] op_sel_hi:[1,0]
	v_pk_add_f32 v[164:165], v[164:165], v[172:173] op_sel_hi:[1,0]
	v_pk_add_f32 v[166:167], v[166:167], v[172:173] op_sel_hi:[1,0]
	v_pk_add_f32 v[168:169], v[168:169], v[172:173] op_sel_hi:[1,0]
	v_rcp_f32_e32 v162, v162
	v_rcp_f32_e32 v163, v163
	v_rcp_f32_e32 v164, v164
	v_rcp_f32_e32 v165, v165
	v_rcp_f32_e32 v166, v166
	v_rcp_f32_e32 v167, v167
	v_rcp_f32_e32 v168, v168
	v_rcp_f32_e32 v169, v169
	v_pk_mul_f32 v[162:163], v[124:125], v[162:163]
	v_pk_mul_f32 v[164:165], v[126:127], v[164:165]
	v_pk_mul_f32 v[166:167], v[92:93], v[166:167]
	v_pk_mul_f32 v[168:169], v[94:95], v[168:169]
	v_pk_mul_f32 v[162:163], v[120:121], v[162:163]
	v_pk_mul_f32 v[164:165], v[122:123], v[164:165]
	v_pk_mul_f32 v[166:167], v[88:89], v[166:167]
	v_pk_mul_f32 v[168:169], v[90:91], v[168:169]
	v_cvt_pk_bf16_f32 v150, v162, v163
	v_cvt_pk_bf16_f32 v151, v164, v165
	v_cvt_pk_bf16_f32 v152, v166, v167
	v_cvt_pk_bf16_f32 v153, v168, v169
	global_store_dwordx4 v[144:145], v[150:153], off
	v_add_co_u32_e32 v146, vcc, s65, v144
	s_nop 0
	v_addc_co_u32_e32 v147, vcc, 0, v145, vcc
	v_pk_mul_f32 v[162:163], v[116:117], v[170:171] op_sel_hi:[1,0]
	v_pk_mul_f32 v[164:165], v[118:119], v[170:171] op_sel_hi:[1,0]
	v_pk_mul_f32 v[166:167], v[84:85], v[170:171] op_sel_hi:[1,0]
	v_pk_mul_f32 v[168:169], v[86:87], v[170:171] op_sel_hi:[1,0]
	v_exp_f32_e32 v162, v162
	v_exp_f32_e32 v163, v163
	v_exp_f32_e32 v164, v164
	v_exp_f32_e32 v165, v165
	v_exp_f32_e32 v166, v166
	v_exp_f32_e32 v167, v167
	v_exp_f32_e32 v168, v168
	v_exp_f32_e32 v169, v169
	v_pk_add_f32 v[162:163], v[162:163], v[172:173] op_sel_hi:[1,0]
	v_pk_add_f32 v[164:165], v[164:165], v[172:173] op_sel_hi:[1,0]
; __device__ __forceinline__ unsigned cvt_pk_bf16(float lo, float hi) { unsigned r; asm volatile("v_cvt_pk_bf16_f32 %0, %1, %2" : "=v"(r) : "v"(lo), "v"(hi)); return r; }
; template <class Epi>
; __device__ __forceinline__ void gemm_phase(LAS unsigned char* lds, const Gemm g, const Sched& S, const Epi& E) {
;     ...
; #pragma unroll
;         for (int a = 0; a < 2; ++a)
; #pragma unroll
;             for (int b = 0; b < 2; ++b)
; #pragma unroll
;                 for (int m = 0; m < 4; ++m)
; #pragma unroll
;                     for (int n = 0; n < 2; ++n) acc[a][b][m][n] = (f32x4){0.f, 0.f, 0.f, 0.f};
;     __device__ __forceinline__ void operator()(AccRef acc, const Unit& u, int wr, int wc, int fr, int fq) const {
;     ...
;             for (int m = 0; m < 4; ++m) { const size_t row = (size_t)u.pm * 256 + ai * 128 + wr * 64 + m * 16 + fr; float o[8];
; #pragma unroll
;                 for (int bj = 0; bj < 2; ++bj) { const f32x4 gg = acc[ai][bj][m][0], uu = acc[ai][bj][m][1];
; #pragma unroll
;                     for (int j = 0; j < 4; ++j) o[4 * bj + j] = gg[j] * __builtin_amdgcn_rcpf(1.0f + __expf(-gg[j])) * uu[j]; }
;                 u32x4 w; w.x = cvt_pk_bf16(o[0], o[1]); w.y = cvt_pk_bf16(o[2], o[3]); w.z = cvt_pk_bf16(o[4], o[5]); w.w = cvt_pk_bf16(o[6], o[7]);
;                 *(u32x4*)(act + row * FF_ + (u.pn * 4 + wc) * 32 + 8 * fq) = w; }
	v_pk_add_f32 v[166:167], v[166:167], v[172:173] op_sel_hi:[1,0]
	v_pk_add_f32 v[168:169], v[168:169], v[172:173] op_sel_hi:[1,0]
	v_rcp_f32_e32 v162, v162
	v_rcp_f32_e32 v163, v163
	v_rcp_f32_e32 v164, v164
	v_rcp_f32_e32 v165, v165
	v_rcp_f32_e32 v166, v166
	v_rcp_f32_e32 v167, v167
	v_rcp_f32_e32 v168, v168
	v_rcp_f32_e32 v169, v169
	v_pk_mul_f32 v[162:163], v[116:117], v[162:163]
	v_pk_mul_f32 v[164:165], v[118:119], v[164:165]
	v_pk_mul_f32 v[166:167], v[84:85], v[166:167]
	v_pk_mul_f32 v[168:169], v[86:87], v[168:169]
	v_pk_mul_f32 v[162:163], v[112:113], v[162:163]
	v_pk_mul_f32 v[164:165], v[114:115], v[164:165]
	v_pk_mul_f32 v[166:167], v[80:81], v[166:167]
	v_pk_mul_f32 v[168:169], v[82:83], v[168:169]
	v_cvt_pk_bf16_f32 v150, v162, v163
	v_cvt_pk_bf16_f32 v151, v164, v165
	v_cvt_pk_bf16_f32 v152, v166, v167
	v_cvt_pk_bf16_f32 v153, v168, v169
	global_store_dwordx4 v[146:147], v[150:153], off
	v_mfma_f32_32x32x16_bf16 v[80:95], v[176:179], v[176:179], 0
	v_mfma_f32_32x32x16_bf16 v[112:127], v[176:179], v[176:179], 0
	v_add_co_u32_e32 v146, vcc, s66, v144
	s_nop 0
	v_addc_co_u32_e32 v147, vcc, 0, v145, vcc
	v_pk_mul_f32 v[162:163], v[108:109], v[170:171] op_sel_hi:[1,0]
	v_pk_mul_f32 v[164:165], v[110:111], v[170:171] op_sel_hi:[1,0]
	v_pk_mul_f32 v[166:167], v[76:77], v[170:171] op_sel_hi:[1,0]
	v_pk_mul_f32 v[168:169], v[78:79], v[170:171] op_sel_hi:[1,0]
	v_exp_f32_e32 v162, v162
	v_exp_f32_e32 v163, v163
	v_exp_f32_e32 v164, v164
	v_exp_f32_e32 v165, v165
	v_exp_f32_e32 v166, v166
	v_exp_f32_e32 v167, v167
	v_exp_f32_e32 v168, v168
	v_exp_f32_e32 v169, v169
	v_pk_add_f32 v[162:163], v[162:163], v[172:173] op_sel_hi:[1,0]
	v_pk_add_f32 v[164:165], v[164:165], v[172:173] op_sel_hi:[1,0]
	v_pk_add_f32 v[166:167], v[166:167], v[172:173] op_sel_hi:[1,0]
	v_pk_add_f32 v[168:169], v[168:169], v[172:173] op_sel_hi:[1,0]
	v_rcp_f32_e32 v162, v162
	v_rcp_f32_e32 v163, v163
	v_rcp_f32_e32 v164, v164
	v_rcp_f32_e32 v165, v165
	v_rcp_f32_e32 v166, v166
	v_rcp_f32_e32 v167, v167
	v_rcp_f32_e32 v168, v168
	v_rcp_f32_e32 v169, v169
	v_pk_mul_f32 v[162:163], v[108:109], v[162:163]
	v_pk_mul_f32 v[164:165], v[110:111], v[164:165]
	v_pk_mul_f32 v[166:167], v[76:77], v[166:167]
	v_pk_mul_f32 v[168:169], v[78:79], v[168:169]
	v_pk_mul_f32 v[162:163], v[104:105], v[162:163]
	v_pk_mul_f32 v[164:165], v[106:107], v[164:165]
	v_pk_mul_f32 v[166:167], v[72:73], v[166:167]
	v_pk_mul_f32 v[168:169], v[74:75], v[168:169]
	v_cvt_pk_bf16_f32 v150, v162, v163
	v_cvt_pk_bf16_f32 v151, v164, v165
	v_cvt_pk_bf16_f32 v152, v166, v167
	v_cvt_pk_bf16_f32 v153, v168, v169
	global_store_dwordx4 v[146:147], v[150:153], off
	v_add_co_u32_e32 v146, vcc, s67, v144
	s_nop 0
	v_addc_co_u32_e32 v147, vcc, 0, v145, vcc
	v_pk_mul_f32 v[162:163], v[100:101], v[170:171] op_sel_hi:[1,0]
	v_pk_mul_f32 v[164:165], v[102:103], v[170:171] op_sel_hi:[1,0]
	v_pk_mul_f32 v[166:167], v[68:69], v[170:171] op_sel_hi:[1,0]
	v_pk_mul_f32 v[168:169], v[70:71], v[170:171] op_sel_hi:[1,0]
	v_exp_f32_e32 v162, v162
	v_exp_f32_e32 v163, v163
	v_exp_f32_e32 v164, v164
	v_exp_f32_e32 v165, v165
	v_exp_f32_e32 v166, v166
	v_exp_f32_e32 v167, v167
	v_exp_f32_e32 v168, v168
	v_exp_f32_e32 v169, v169
	v_pk_add_f32 v[162:163], v[162:163], v[172:173] op_sel_hi:[1,0]
	v_pk_add_f32 v[164:165], v[164:165], v[172:173] op_sel_hi:[1,0]
	v_pk_add_f32 v[166:167], v[166:167], v[172:173] op_sel_hi:[1,0]
	v_pk_add_f32 v[168:169], v[168:169], v[172:173] op_sel_hi:[1,0]
	v_rcp_f32_e32 v162, v162
	v_rcp_f32_e32 v163, v163
	v_rcp_f32_e32 v164, v164
	v_rcp_f32_e32 v165, v165
	v_rcp_f32_e32 v166, v166
	v_rcp_f32_e32 v167, v167
	v_rcp_f32_e32 v168, v168
	v_rcp_f32_e32 v169, v169
	v_pk_mul_f32 v[162:163], v[100:101], v[162:163]
	v_pk_mul_f32 v[164:165], v[102:103], v[164:165]
	v_pk_mul_f32 v[166:167], v[68:69], v[166:167]
	v_pk_mul_f32 v[168:169], v[70:71], v[168:169]
	v_pk_mul_f32 v[162:163], v[96:97], v[162:163]
	v_pk_mul_f32 v[164:165], v[98:99], v[164:165]
	v_pk_mul_f32 v[166:167], v[64:65], v[166:167]
	v_pk_mul_f32 v[168:169], v[66:67], v[168:169]
	v_cvt_pk_bf16_f32 v150, v162, v163
	v_cvt_pk_bf16_f32 v151, v164, v165
	v_cvt_pk_bf16_f32 v152, v166, v167
	v_cvt_pk_bf16_f32 v153, v168, v169
	global_store_dwordx4 v[146:147], v[150:153], off
	v_mfma_f32_32x32x16_bf16 v[64:79], v[176:179], v[176:179], 0
	v_mfma_f32_32x32x16_bf16 v[96:111], v[176:179], v[176:179], 0
	v_add_co_u32_e32 v146, vcc, s70, v144
	s_nop 0
	v_addc_co_u32_e32 v147, vcc, 0, v145, vcc
	v_pk_mul_f32 v[162:163], v[60:61], v[170:171] op_sel_hi:[1,0]
	v_pk_mul_f32 v[164:165], v[62:63], v[170:171] op_sel_hi:[1,0]
	v_pk_mul_f32 v[166:167], v[28:29], v[170:171] op_sel_hi:[1,0]
	v_pk_mul_f32 v[168:169], v[30:31], v[170:171] op_sel_hi:[1,0]
	v_exp_f32_e32 v162, v162
	v_exp_f32_e32 v163, v163
	v_exp_f32_e32 v164, v164
	v_exp_f32_e32 v165, v165
	v_exp_f32_e32 v166, v166
	v_exp_f32_e32 v167, v167
	v_exp_f32_e32 v168, v168
	v_exp_f32_e32 v169, v169
	v_pk_add_f32 v[162:163], v[162:163], v[172:173] op_sel_hi:[1,0]
	v_pk_add_f32 v[164:165], v[164:165], v[172:173] op_sel_hi:[1,0]
	v_pk_add_f32 v[166:167], v[166:167], v[172:173] op_sel_hi:[1,0]
	v_pk_add_f32 v[168:169], v[168:169], v[172:173] op_sel_hi:[1,0]
	v_rcp_f32_e32 v162, v162
	v_rcp_f32_e32 v163, v163
	v_rcp_f32_e32 v164, v164
	v_rcp_f32_e32 v165, v165
	v_rcp_f32_e32 v166, v166
	v_rcp_f32_e32 v167, v167
	v_rcp_f32_e32 v168, v168
	v_rcp_f32_e32 v169, v169
	v_pk_mul_f32 v[162:163], v[60:61], v[162:163]
	v_pk_mul_f32 v[164:165], v[62:63], v[164:165]
	v_pk_mul_f32 v[166:167], v[28:29], v[166:167]
	v_pk_mul_f32 v[168:169], v[30:31], v[168:169]
; __device__ __forceinline__ unsigned cvt_pk_bf16(float lo, float hi) { unsigned r; asm volatile("v_cvt_pk_bf16_f32 %0, %1, %2" : "=v"(r) : "v"(lo), "v"(hi)); return r; }
; template <class Epi>
; __device__ __forceinline__ void gemm_phase(LAS unsigned char* lds, const Gemm g, const Sched& S, const Epi& E) {
;     ...
;         if (!has_next) break;
; #pragma unroll
;         for (int a = 0; a < 2; ++a)
; #pragma unroll
;             for (int b = 0; b < 2; ++b)
; #pragma unroll
;                 for (int m = 0; m < 4; ++m)
; #pragma unroll
;                     for (int n = 0; n < 2; ++n) acc[a][b][m][n] = (f32x4){0.f, 0.f, 0.f, 0.f};
;         cur = nxt; cA = nA; cB = nB; ++ui;
;     __device__ __forceinline__ void operator()(AccRef acc, const Unit& u, int wr, int wc, int fr, int fq) const {
;     ...
;             for (int m = 0; m < 4; ++m) { const size_t row = (size_t)u.pm * 256 + ai * 128 + wr * 64 + m * 16 + fr; float o[8];
; #pragma unroll
;                 for (int bj = 0; bj < 2; ++bj) { const f32x4 gg = acc[ai][bj][m][0], uu = acc[ai][bj][m][1];
; #pragma unroll
;                     for (int j = 0; j < 4; ++j) o[4 * bj + j] = gg[j] * __builtin_amdgcn_rcpf(1.0f + __expf(-gg[j])) * uu[j]; }
;                 u32x4 w; w.x = cvt_pk_bf16(o[0], o[1]); w.y = cvt_pk_bf16(o[2], o[3]); w.z = cvt_pk_bf16(o[4], o[5]); w.w = cvt_pk_bf16(o[6], o[7]);
;                 *(u32x4*)(act + row * FF_ + (u.pn * 4 + wc) * 32 + 8 * fq) = w; }
	v_pk_mul_f32 v[162:163], v[56:57], v[162:163]
	v_pk_mul_f32 v[164:165], v[58:59], v[164:165]
	v_pk_mul_f32 v[166:167], v[24:25], v[166:167]
	v_pk_mul_f32 v[168:169], v[26:27], v[168:169]
	v_cvt_pk_bf16_f32 v150, v162, v163
	v_cvt_pk_bf16_f32 v151, v164, v165
	v_cvt_pk_bf16_f32 v152, v166, v167
	v_cvt_pk_bf16_f32 v153, v168, v169
	global_store_dwordx4 v[146:147], v[150:153], off
	v_add_co_u32_e32 v146, vcc, s71, v144
	s_nop 0
	v_addc_co_u32_e32 v147, vcc, 0, v145, vcc
	v_pk_mul_f32 v[162:163], v[52:53], v[170:171] op_sel_hi:[1,0]
	v_pk_mul_f32 v[164:165], v[54:55], v[170:171] op_sel_hi:[1,0]
	v_pk_mul_f32 v[166:167], v[20:21], v[170:171] op_sel_hi:[1,0]
	v_pk_mul_f32 v[168:169], v[22:23], v[170:171] op_sel_hi:[1,0]
	v_exp_f32_e32 v162, v162
	v_exp_f32_e32 v163, v163
	v_exp_f32_e32 v164, v164
	v_exp_f32_e32 v165, v165
	v_exp_f32_e32 v166, v166
	v_exp_f32_e32 v167, v167
	v_exp_f32_e32 v168, v168
	v_exp_f32_e32 v169, v169
	v_pk_add_f32 v[162:163], v[162:163], v[172:173] op_sel_hi:[1,0]
	v_pk_add_f32 v[164:165], v[164:165], v[172:173] op_sel_hi:[1,0]
	v_pk_add_f32 v[166:167], v[166:167], v[172:173] op_sel_hi:[1,0]
	v_pk_add_f32 v[168:169], v[168:169], v[172:173] op_sel_hi:[1,0]
	v_rcp_f32_e32 v162, v162
	v_rcp_f32_e32 v163, v163
	v_rcp_f32_e32 v164, v164
	v_rcp_f32_e32 v165, v165
	v_rcp_f32_e32 v166, v166
	v_rcp_f32_e32 v167, v167
	v_rcp_f32_e32 v168, v168
	v_rcp_f32_e32 v169, v169
	v_pk_mul_f32 v[162:163], v[52:53], v[162:163]
	v_pk_mul_f32 v[164:165], v[54:55], v[164:165]
	v_pk_mul_f32 v[166:167], v[20:21], v[166:167]
	v_pk_mul_f32 v[168:169], v[22:23], v[168:169]
	v_pk_mul_f32 v[162:163], v[48:49], v[162:163]
	v_pk_mul_f32 v[164:165], v[50:51], v[164:165]
	v_pk_mul_f32 v[166:167], v[16:17], v[166:167]
	v_pk_mul_f32 v[168:169], v[18:19], v[168:169]
	v_cvt_pk_bf16_f32 v150, v162, v163
	v_cvt_pk_bf16_f32 v151, v164, v165
	v_cvt_pk_bf16_f32 v152, v166, v167
	v_cvt_pk_bf16_f32 v153, v168, v169
	global_store_dwordx4 v[146:147], v[150:153], off
	v_mfma_f32_32x32x16_bf16 v[16:31], v[176:179], v[176:179], 0
	v_mfma_f32_32x32x16_bf16 v[48:63], v[176:179], v[176:179], 0
	v_add_co_u32_e32 v146, vcc, s78, v144
	s_nop 0
	v_addc_co_u32_e32 v147, vcc, 0, v145, vcc
	v_pk_mul_f32 v[162:163], v[44:45], v[170:171] op_sel_hi:[1,0]
	v_pk_mul_f32 v[164:165], v[46:47], v[170:171] op_sel_hi:[1,0]
	v_pk_mul_f32 v[166:167], v[12:13], v[170:171] op_sel_hi:[1,0]
	v_pk_mul_f32 v[168:169], v[14:15], v[170:171] op_sel_hi:[1,0]
	v_exp_f32_e32 v162, v162
	v_exp_f32_e32 v163, v163
	v_exp_f32_e32 v164, v164
	v_exp_f32_e32 v165, v165
	v_exp_f32_e32 v166, v166
	v_exp_f32_e32 v167, v167
	v_exp_f32_e32 v168, v168
	v_exp_f32_e32 v169, v169
	v_pk_add_f32 v[162:163], v[162:163], v[172:173] op_sel_hi:[1,0]
	v_pk_add_f32 v[164:165], v[164:165], v[172:173] op_sel_hi:[1,0]
	v_pk_add_f32 v[166:167], v[166:167], v[172:173] op_sel_hi:[1,0]
	v_pk_add_f32 v[168:169], v[168:169], v[172:173] op_sel_hi:[1,0]
	v_rcp_f32_e32 v162, v162
	v_rcp_f32_e32 v163, v163
	v_rcp_f32_e32 v164, v164
	v_rcp_f32_e32 v165, v165
	v_rcp_f32_e32 v166, v166
	v_rcp_f32_e32 v167, v167
	v_rcp_f32_e32 v168, v168
	v_rcp_f32_e32 v169, v169
	v_pk_mul_f32 v[162:163], v[44:45], v[162:163]
	v_pk_mul_f32 v[164:165], v[46:47], v[164:165]
	v_pk_mul_f32 v[166:167], v[12:13], v[166:167]
	v_pk_mul_f32 v[168:169], v[14:15], v[168:169]
	v_pk_mul_f32 v[162:163], v[40:41], v[162:163]
	v_pk_mul_f32 v[164:165], v[42:43], v[164:165]
	v_pk_mul_f32 v[166:167], v[8:9], v[166:167]
	v_pk_mul_f32 v[168:169], v[10:11], v[168:169]
	v_cvt_pk_bf16_f32 v150, v162, v163
	v_cvt_pk_bf16_f32 v151, v164, v165
	v_cvt_pk_bf16_f32 v152, v166, v167
	v_cvt_pk_bf16_f32 v153, v168, v169
	global_store_dwordx4 v[146:147], v[150:153], off
	v_add_co_u32_e32 v144, vcc, 0x1e4000, v144
	v_addc_co_u32_e32 v145, vcc, 0, v145, vcc
	s_andn2_b64 vcc, exec, s[10:11]
	v_pk_mul_f32 v[162:163], v[36:37], v[170:171] op_sel_hi:[1,0]
	v_pk_mul_f32 v[164:165], v[38:39], v[170:171] op_sel_hi:[1,0]
	v_pk_mul_f32 v[166:167], v[4:5], v[170:171] op_sel_hi:[1,0]
	v_pk_mul_f32 v[168:169], v[6:7], v[170:171] op_sel_hi:[1,0]
	v_exp_f32_e32 v162, v162
	v_exp_f32_e32 v163, v163
	v_exp_f32_e32 v164, v164
	v_exp_f32_e32 v165, v165
	v_exp_f32_e32 v166, v166
	v_exp_f32_e32 v167, v167
	v_exp_f32_e32 v168, v168
	v_exp_f32_e32 v169, v169
	v_pk_add_f32 v[162:163], v[162:163], v[172:173] op_sel_hi:[1,0]
	v_pk_add_f32 v[164:165], v[164:165], v[172:173] op_sel_hi:[1,0]
	v_pk_add_f32 v[166:167], v[166:167], v[172:173] op_sel_hi:[1,0]
	v_pk_add_f32 v[168:169], v[168:169], v[172:173] op_sel_hi:[1,0]
	v_rcp_f32_e32 v162, v162
	v_rcp_f32_e32 v163, v163
	v_rcp_f32_e32 v164, v164
	v_rcp_f32_e32 v165, v165
	v_rcp_f32_e32 v166, v166
	v_rcp_f32_e32 v167, v167
	v_rcp_f32_e32 v168, v168
	v_rcp_f32_e32 v169, v169
	v_pk_mul_f32 v[162:163], v[36:37], v[162:163]
	v_pk_mul_f32 v[164:165], v[38:39], v[164:165]
	v_pk_mul_f32 v[166:167], v[4:5], v[166:167]
	v_pk_mul_f32 v[168:169], v[6:7], v[168:169]
	v_pk_mul_f32 v[162:163], v[32:33], v[162:163]
	v_pk_mul_f32 v[164:165], v[34:35], v[164:165]
	v_pk_mul_f32 v[166:167], v[0:1], v[166:167]
	v_pk_mul_f32 v[168:169], v[2:3], v[168:169]
	v_cvt_pk_bf16_f32 v150, v162, v163
	v_cvt_pk_bf16_f32 v151, v164, v165
	v_cvt_pk_bf16_f32 v152, v166, v167
	v_cvt_pk_bf16_f32 v153, v168, v169
	global_store_dwordx4 v[144:145], v[150:153], off
	v_mfma_f32_32x32x16_bf16 v[0:15], v[176:179], v[176:179], 0
	v_mfma_f32_32x32x16_bf16 v[32:47], v[176:179], v[176:179], 0
	s_cbranch_vccz .LBB0_2084
	s_mov_b64 s[22:23], s[36:37]
	s_andn2_b64 vcc, exec, s[8:9]
	s_mov_b64 s[36:37], s[22:23]
	s_cbranch_vccnz .LBB0_2085

; template <class Epi>
; __device__ __forceinline__ void gemm_phase(LAS unsigned char* lds, const Gemm g, const Sched& S, const Epi& E) {
;     ...
; #pragma unroll
;         for (int a = 0; a < 2; ++a)
; #pragma unroll
;             for (int b = 0; b < 2; ++b)
; #pragma unroll
;                 for (int m = 0; m < 4; ++m)
; #pragma unroll
;                     for (int n = 0; n < 2; ++n) acc[a][b][m][n] = (f32x4){0.f, 0.f, 0.f, 0.f};
;         cur = nxt; cA = nA; cB = nB; ++ui;
.LBB0_3081:
	s_mov_b32 s50, s16
	s_mov_b32 s10, s18
	s_mov_b64 s[12:13], s[22:23]
	s_mov_b32 s47, s63
	s_andn2_b64 vcc, exec, s[6:7]
	s_mov_b64 s[24:25], s[20:21]
	s_cbranch_vccz .LBB0_3088

; #define PG8_STAGE(bufoff, gbase, voff) do { _Pragma("unroll") for (int _i = 0; _i < 2; ++_i) \
;         __builtin_amdgcn_global_load_lds((const unsigned*)((const char*)(gbase) + (voff)[_i]), (LAS unsigned*)(lds + (bufoff) + ldsw + _i * 8192), 16, 0, 0); } while (0)
; #define PG8_LDA(dst, b, h) do { _Pragma("unroll") for (int m = 0; m < 4; ++m) _Pragma("unroll") for (int k = 0; k < 2; ++k) dst[m][k] = *(const LAS bf16x8*)(lds + PG8_SA(b, h) + aoff + m * 2048 + k * 1024); } while (0)
; #define PG8_LDB(dst, b, h) do { _Pragma("unroll") for (int n = 0; n < 2; ++n) _Pragma("unroll") for (int k = 0; k < 2; ++k) dst[n][k] = *(const LAS bf16x8*)(lds + PG8_SB(b, h) + boff + n * 2048 + k * 1024); } while (0)
; #define PG8_MMA(ai, bj, At, Bt) do { __builtin_amdgcn_s_setprio(1); _Pragma("unroll") for (int m = 0; m < 4; ++m) _Pragma("unroll") for (int n = 0; n < 2; ++n) _Pragma("unroll") for (int k = 0; k < 2; ++k) \
;         acc[ai][bj][m][n] = __builtin_amdgcn_mfma_f32_16x16x32_bf16(Bt[n][k], At[m][k], acc[ai][bj][m][n], 0, 0, 0); __builtin_amdgcn_s_setprio(0); } while (0)
; #define PG8_WAIT_L(n) asm volatile("s_waitcnt lgkmcnt(" #n ")" ::: "memory")
; #define PG8_BAR __builtin_amdgcn_s_barrier()
; #define PG8_SCHED __builtin_amdgcn_sched_barrier(0)
; template <class Epi>
; __device__ __forceinline__ void gemm_phase(LAS unsigned char* lds, const Gemm g, const Sched& S, const Epi& E) {
;     ...
;             PG8_LDB(B0, 0, 0); PG8_SCHED; PG8_LDA(At, 0, 0); PG8_STAGE(PG8_SA(1, 1), a1 + hstepA, voffA);
;             PG8_WAIT_L(8); PG8_BAR; PG8_WAIT_L(0); PG8_MMA(0, 0, At, B0); PG8_BAR; PG8_SCHED;
;             PG8_LDB(B1, 0, 1); PG8_STAGE(PG8_SB(0, 0), b2, voffB);
;             PG8_BAR; PG8_WAIT_L(0); PG8_MMA(0, 1, At, B1); PG8_BAR;
;             PG8_LDA(At, 0, 1); PG8_STAGE(PG8_SA(0, 0), a2, voffA);
;             PG8_BAR; PG8_WAIT_L(0); PG8_MMA(1, 0, At, B0); PG8_BAR; PG8_SCHED;
.LBB0_3085:
	v_add_u32_e32 v162, s54, v148
	s_add_u32 s36, s12, s24
	ds_read_b128 v[150:153], v162
	ds_read_b128 v[154:157], v162 offset:1024
	ds_read_b128 v[158:161], v162 offset:2048
	ds_read_b128 v[162:165], v162 offset:3072
	s_addc_u32 s37, s13, s25
	s_add_u32 s36, s36, 0x100
	s_addc_u32 s37, s37, 0
	s_add_u32 s70, s11, s24
	s_addc_u32 s71, s64, s25
	s_cmpk_eq_i32 s24, 0xf00
	s_cselect_b32 s39, s19, s37
	s_cselect_b32 s38, s65, s36
	s_cselect_b32 s37, s17, s71
	s_cselect_b32 s36, s66, s70
	v_lshl_add_u64 v[190:191], v[144:145], 0, s[24:25]
	s_add_i32 m0, s40, 0xc000
	ds_read_b128 v[166:169], v149
	ds_read_b128 v[170:173], v149 offset:1024
	ds_read_b128 v[174:177], v149 offset:2048
	ds_read_b128 v[178:181], v149 offset:3072
	ds_read_b128 v[182:185], v149 offset:4096
	ds_read_b128 v[186:189], v149 offset:5120
	ds_read_b128 v[194:197], v149 offset:6144
	ds_read_b128 v[198:201], v149 offset:7168
	global_load_lds_dwordx4 v[190:191], off
	v_lshl_add_u64 v[190:191], v[146:147], 0, s[24:25]
	s_add_i32 m0, s40, 0xe000
	s_nop 0
	global_load_lds_dwordx4 v[190:191], off
	s_waitcnt lgkmcnt(8)
	s_barrier
	s_waitcnt lgkmcnt(0)
	s_setprio 1
	s_waitcnt lgkmcnt(0)
	v_mfma_f32_16x16x32_bf16 v[124:127], v[150:153], v[166:169], v[124:127]
	v_mfma_f32_16x16x32_bf16 v[120:123], v[158:161], v[166:169], v[120:123]
	v_mfma_f32_16x16x32_bf16 v[116:119], v[150:153], v[174:177], v[116:119]
	v_mfma_f32_16x16x32_bf16 v[112:115], v[158:161], v[174:177], v[112:115]
	v_mfma_f32_16x16x32_bf16 v[108:111], v[150:153], v[182:185], v[108:111]
	v_mfma_f32_16x16x32_bf16 v[104:107], v[158:161], v[182:185], v[104:107]
	v_mfma_f32_16x16x32_bf16 v[100:103], v[150:153], v[194:197], v[100:103]
	v_mfma_f32_16x16x32_bf16 v[96:99], v[158:161], v[194:197], v[96:99]
	v_mfma_f32_16x16x32_bf16 v[124:127], v[154:157], v[170:173], v[124:127]
	v_mfma_f32_16x16x32_bf16 v[120:123], v[162:165], v[170:173], v[120:123]
	v_mfma_f32_16x16x32_bf16 v[116:119], v[154:157], v[178:181], v[116:119]
	v_mfma_f32_16x16x32_bf16 v[112:115], v[162:165], v[178:181], v[112:115]
	v_mfma_f32_16x16x32_bf16 v[108:111], v[154:157], v[186:189], v[108:111]
	v_mfma_f32_16x16x32_bf16 v[104:107], v[162:165], v[186:189], v[104:107]
	v_mfma_f32_16x16x32_bf16 v[100:103], v[154:157], v[198:201], v[100:103]
	v_mfma_f32_16x16x32_bf16 v[96:99], v[162:165], v[198:201], v[96:99]
	s_setprio 0
	s_barrier
	v_add_u32_e32 v190, s55, v148
	s_add_i32 s70, s54, s34
	ds_read_b128 v[202:205], v190
	ds_read_b128 v[206:209], v190 offset:1024
	ds_read_b128 v[210:213], v190 offset:2048
	ds_read_b128 v[214:217], v190 offset:3072
	v_lshl_add_u64 v[190:191], s[36:37], 0, v[130:131]
	s_mov_b32 m0, s70
	v_lshl_add_u64 v[218:219], s[36:37], 0, v[128:129]
	global_load_lds_dwordx4 v[190:191], off
	s_add_i32 m0, s70, 0x2000
	s_nop 0
	global_load_lds_dwordx4 v[218:219], off
	s_barrier
	s_waitcnt lgkmcnt(0)
	s_setprio 1
	s_waitcnt lgkmcnt(0)
	v_mfma_f32_16x16x32_bf16 v[92:95], v[202:205], v[166:169], v[92:95]
	v_mfma_f32_16x16x32_bf16 v[88:91], v[210:213], v[166:169], v[88:91]
	v_mfma_f32_16x16x32_bf16 v[84:87], v[202:205], v[174:177], v[84:87]
	v_mfma_f32_16x16x32_bf16 v[80:83], v[210:213], v[174:177], v[80:83]
	v_mfma_f32_16x16x32_bf16 v[76:79], v[202:205], v[182:185], v[76:79]
	v_mfma_f32_16x16x32_bf16 v[72:75], v[210:213], v[182:185], v[72:75]
	v_mfma_f32_16x16x32_bf16 v[68:71], v[202:205], v[194:197], v[68:71]
	v_mfma_f32_16x16x32_bf16 v[64:67], v[210:213], v[194:197], v[64:67]
	v_mfma_f32_16x16x32_bf16 v[92:95], v[206:209], v[170:173], v[92:95]
	v_mfma_f32_16x16x32_bf16 v[88:91], v[214:217], v[170:173], v[88:91]
	v_mfma_f32_16x16x32_bf16 v[84:87], v[206:209], v[178:181], v[84:87]
	v_mfma_f32_16x16x32_bf16 v[80:83], v[214:217], v[178:181], v[80:83]
	v_mfma_f32_16x16x32_bf16 v[76:79], v[206:209], v[186:189], v[76:79]
	v_mfma_f32_16x16x32_bf16 v[72:75], v[214:217], v[186:189], v[72:75]
	v_mfma_f32_16x16x32_bf16 v[68:71], v[206:209], v[198:201], v[68:71]
	v_mfma_f32_16x16x32_bf16 v[64:67], v[214:217], v[198:201], v[64:67]
	s_setprio 0
	s_mov_b32 m0, s40
	v_lshl_add_u64 v[220:221], s[38:39], 0, v[130:131]
	s_barrier
	ds_read_b128 v[166:169], v149 offset:16384
	ds_read_b128 v[170:173], v149 offset:17408
	ds_read_b128 v[174:177], v149 offset:18432
	ds_read_b128 v[178:181], v149 offset:19456
	ds_read_b128 v[182:185], v149 offset:20480
	ds_read_b128 v[186:189], v149 offset:21504
	ds_read_b128 v[194:197], v149 offset:22528
	ds_read_b128 v[198:201], v149 offset:23552
	global_load_lds_dwordx4 v[220:221], off
	v_lshl_add_u64 v[222:223], s[38:39], 0, v[128:129]
	s_mov_b32 m0, s41
	s_nop 0
	global_load_lds_dwordx4 v[222:223], off
	s_barrier
	s_waitcnt lgkmcnt(0)
	s_setprio 1
	s_waitcnt lgkmcnt(0)
	v_mfma_f32_16x16x32_bf16 v[60:63], v[150:153], v[166:169], v[60:63]
	v_mfma_f32_16x16x32_bf16 v[56:59], v[158:161], v[166:169], v[56:59]
	v_mfma_f32_16x16x32_bf16 v[52:55], v[150:153], v[174:177], v[52:55]
	v_mfma_f32_16x16x32_bf16 v[48:51], v[158:161], v[174:177], v[48:51]
	v_mfma_f32_16x16x32_bf16 v[44:47], v[150:153], v[182:185], v[44:47]
	v_mfma_f32_16x16x32_bf16 v[40:43], v[158:161], v[182:185], v[40:43]
	v_mfma_f32_16x16x32_bf16 v[36:39], v[150:153], v[194:197], v[36:39]
	v_mfma_f32_16x16x32_bf16 v[32:35], v[158:161], v[194:197], v[32:35]
	v_mfma_f32_16x16x32_bf16 v[60:63], v[154:157], v[170:173], v[60:63]
	v_mfma_f32_16x16x32_bf16 v[56:59], v[162:165], v[170:173], v[56:59]
	v_mfma_f32_16x16x32_bf16 v[52:55], v[154:157], v[178:181], v[52:55]
	v_mfma_f32_16x16x32_bf16 v[48:51], v[162:165], v[178:181], v[48:51]
	v_mfma_f32_16x16x32_bf16 v[44:47], v[154:157], v[186:189], v[44:47]
	v_mfma_f32_16x16x32_bf16 v[40:43], v[162:165], v[186:189], v[40:43]
	v_mfma_f32_16x16x32_bf16 v[36:39], v[154:157], v[198:201], v[36:39]
	v_mfma_f32_16x16x32_bf16 v[32:35], v[162:165], v[198:201], v[32:35]
	s_setprio 0
	s_barrier
; #define PG8_STAGE(bufoff, gbase, voff) do { _Pragma("unroll") for (int _i = 0; _i < 2; ++_i) \
;         __builtin_amdgcn_global_load_lds((const unsigned*)((const char*)(gbase) + (voff)[_i]), (LAS unsigned*)(lds + (bufoff) + ldsw + _i * 8192), 16, 0, 0); } while (0)
; #define PG8_LDA(dst, b, h) do { _Pragma("unroll") for (int m = 0; m < 4; ++m) _Pragma("unroll") for (int k = 0; k < 2; ++k) dst[m][k] = *(const LAS bf16x8*)(lds + PG8_SA(b, h) + aoff + m * 2048 + k * 1024); } while (0)
; #define PG8_LDB(dst, b, h) do { _Pragma("unroll") for (int n = 0; n < 2; ++n) _Pragma("unroll") for (int k = 0; k < 2; ++k) dst[n][k] = *(const LAS bf16x8*)(lds + PG8_SB(b, h) + boff + n * 2048 + k * 1024); } while (0)
; #define PG8_MMA(ai, bj, At, Bt) do { __builtin_amdgcn_s_setprio(1); _Pragma("unroll") for (int m = 0; m < 4; ++m) _Pragma("unroll") for (int n = 0; n < 2; ++n) _Pragma("unroll") for (int k = 0; k < 2; ++k) \
;         acc[ai][bj][m][n] = __builtin_amdgcn_mfma_f32_16x16x32_bf16(Bt[n][k], At[m][k], acc[ai][bj][m][n], 0, 0, 0); __builtin_amdgcn_s_setprio(0); } while (0)
; #define PG8_WAIT_V(n) asm volatile("s_waitcnt vmcnt(" #n ")" ::: "memory")
; #define PG8_WAIT_L(n) asm volatile("s_waitcnt lgkmcnt(" #n ")" ::: "memory")
; #define PG8_BAR __builtin_amdgcn_s_barrier()
; #define PG8_SCHED __builtin_amdgcn_sched_barrier(0)
; template <class Epi>
; __device__ __forceinline__ void gemm_phase(LAS unsigned char* lds, const Gemm g, const Sched& S, const Epi& E) {
;     ...
;             PG8_STAGE(PG8_SB(0, 1), b2 + hstepB, voffB);
;             PG8_WAIT_V(6); PG8_BAR; PG8_MMA(1, 1, At, B1); PG8_BAR;
;             PG8_LDB(B0, 1, 0); PG8_SCHED; PG8_LDA(At, 1, 0); PG8_STAGE(PG8_SA(0, 1), a2 + hstepA, voffA);
;             PG8_WAIT_L(8); PG8_BAR; PG8_WAIT_L(0); PG8_MMA(0, 0, At, B0); PG8_BAR; PG8_SCHED;
;             PG8_LDB(B1, 1, 1); PG8_STAGE(PG8_SB(1, 0), b3, voffB);
;             PG8_BAR; PG8_WAIT_L(0); PG8_MMA(0, 1, At, B1); PG8_BAR;
;             PG8_LDA(At, 1, 1); PG8_STAGE(PG8_SA(1, 0), a3, voffA);
	s_add_u32 s70, s36, 0x80000
	s_addc_u32 s71, s37, 0
	s_add_i32 s72, s55, s34
	v_lshl_add_u64 v[150:151], s[70:71], 0, v[130:131]
	s_mov_b32 m0, s72
	s_nop 0
	global_load_lds_dwordx4 v[150:151], off
	v_lshl_add_u64 v[150:151], s[70:71], 0, v[128:129]
	s_add_i32 m0, s72, 0x2000
	s_nop 0
	global_load_lds_dwordx4 v[150:151], off
	s_waitcnt vmcnt(6)
	s_barrier
	s_setprio 1
	v_mfma_f32_16x16x32_bf16 v[28:31], v[202:205], v[166:169], v[28:31]
	v_mfma_f32_16x16x32_bf16 v[24:27], v[210:213], v[166:169], v[24:27]
	v_mfma_f32_16x16x32_bf16 v[20:23], v[202:205], v[174:177], v[20:23]
	v_mfma_f32_16x16x32_bf16 v[16:19], v[210:213], v[174:177], v[16:19]
	v_mfma_f32_16x16x32_bf16 v[12:15], v[202:205], v[182:185], v[12:15]
	v_mfma_f32_16x16x32_bf16 v[8:11], v[210:213], v[182:185], v[8:11]
	v_mfma_f32_16x16x32_bf16 v[4:7], v[202:205], v[194:197], v[4:7]
	v_mfma_f32_16x16x32_bf16 v[0:3], v[210:213], v[194:197], v[0:3]
	v_mfma_f32_16x16x32_bf16 v[28:31], v[206:209], v[170:173], v[28:31]
	v_mfma_f32_16x16x32_bf16 v[24:27], v[214:217], v[170:173], v[24:27]
	v_mfma_f32_16x16x32_bf16 v[20:23], v[206:209], v[178:181], v[20:23]
	v_mfma_f32_16x16x32_bf16 v[16:19], v[214:217], v[178:181], v[16:19]
	v_mfma_f32_16x16x32_bf16 v[12:15], v[206:209], v[186:189], v[12:15]
	v_mfma_f32_16x16x32_bf16 v[8:11], v[214:217], v[186:189], v[8:11]
	v_mfma_f32_16x16x32_bf16 v[4:7], v[206:209], v[198:201], v[4:7]
	v_mfma_f32_16x16x32_bf16 v[0:3], v[214:217], v[198:201], v[0:3]
	s_setprio 0
	s_add_i32 s70, 0, 0x18000
	v_add_u32_e32 v162, s70, v148
	s_barrier
	ds_read_b128 v[150:153], v162
	ds_read_b128 v[154:157], v162 offset:1024
	ds_read_b128 v[158:161], v162 offset:2048
	ds_read_b128 v[162:165], v162 offset:3072
	s_add_u32 s38, s38, 0x80000
	s_addc_u32 s39, s39, 0
	s_mov_b32 m0, s43
	v_lshl_add_u64 v[202:203], s[38:39], 0, v[130:131]
	ds_read_b128 v[166:169], v149 offset:32768
	ds_read_b128 v[170:173], v149 offset:33792
	ds_read_b128 v[174:177], v149 offset:34816
	ds_read_b128 v[178:181], v149 offset:35840
	ds_read_b128 v[182:185], v149 offset:36864
	ds_read_b128 v[186:189], v149 offset:37888
	ds_read_b128 v[194:197], v149 offset:38912
	ds_read_b128 v[198:201], v149 offset:39936
	global_load_lds_dwordx4 v[202:203], off
	v_lshl_add_u64 v[202:203], s[38:39], 0, v[128:129]
	s_mov_b32 m0, s46
	s_nop 0
	global_load_lds_dwordx4 v[202:203], off
	s_waitcnt lgkmcnt(8)
	s_barrier
	s_waitcnt lgkmcnt(0)
	s_setprio 1
	s_waitcnt lgkmcnt(0)
	v_mfma_f32_16x16x32_bf16 v[124:127], v[150:153], v[166:169], v[124:127]
	v_mfma_f32_16x16x32_bf16 v[120:123], v[158:161], v[166:169], v[120:123]
	v_mfma_f32_16x16x32_bf16 v[116:119], v[150:153], v[174:177], v[116:119]
	v_mfma_f32_16x16x32_bf16 v[112:115], v[158:161], v[174:177], v[112:115]
	v_mfma_f32_16x16x32_bf16 v[108:111], v[150:153], v[182:185], v[108:111]
	v_mfma_f32_16x16x32_bf16 v[104:107], v[158:161], v[182:185], v[104:107]
	v_mfma_f32_16x16x32_bf16 v[100:103], v[150:153], v[194:197], v[100:103]
	v_mfma_f32_16x16x32_bf16 v[96:99], v[158:161], v[194:197], v[96:99]
	v_mfma_f32_16x16x32_bf16 v[124:127], v[154:157], v[170:173], v[124:127]
	v_mfma_f32_16x16x32_bf16 v[120:123], v[162:165], v[170:173], v[120:123]
	v_mfma_f32_16x16x32_bf16 v[116:119], v[154:157], v[178:181], v[116:119]
	v_mfma_f32_16x16x32_bf16 v[112:115], v[162:165], v[178:181], v[112:115]
	v_mfma_f32_16x16x32_bf16 v[108:111], v[154:157], v[186:189], v[108:111]
	v_mfma_f32_16x16x32_bf16 v[104:107], v[162:165], v[186:189], v[104:107]
	v_mfma_f32_16x16x32_bf16 v[100:103], v[154:157], v[198:201], v[100:103]
	v_mfma_f32_16x16x32_bf16 v[96:99], v[162:165], v[198:201], v[96:99]
	s_setprio 0
	s_barrier
	s_add_i32 s38, 0, 0x1c000
	s_add_i32 s39, s70, s34
	v_add_u32_e32 v214, s38, v148
	v_lshl_add_u64 v[190:191], v[190:191], 0, s[14:15]
	s_mov_b32 m0, s39
	ds_read_b128 v[202:205], v214
	ds_read_b128 v[206:209], v214 offset:1024
	ds_read_b128 v[210:213], v214 offset:2048
	ds_read_b128 v[214:217], v214 offset:3072
	global_load_lds_dwordx4 v[190:191], off
	v_lshl_add_u64 v[190:191], v[218:219], 0, s[14:15]
	s_add_i32 m0, s39, 0x2000
	s_nop 0
	global_load_lds_dwordx4 v[190:191], off
	s_barrier
	s_waitcnt lgkmcnt(0)
	s_setprio 1
	s_waitcnt lgkmcnt(0)
	v_mfma_f32_16x16x32_bf16 v[92:95], v[202:205], v[166:169], v[92:95]
	v_mfma_f32_16x16x32_bf16 v[88:91], v[210:213], v[166:169], v[88:91]
	v_mfma_f32_16x16x32_bf16 v[84:87], v[202:205], v[174:177], v[84:87]
	v_mfma_f32_16x16x32_bf16 v[80:83], v[210:213], v[174:177], v[80:83]
	v_mfma_f32_16x16x32_bf16 v[76:79], v[202:205], v[182:185], v[76:79]
	v_mfma_f32_16x16x32_bf16 v[72:75], v[210:213], v[182:185], v[72:75]
	v_mfma_f32_16x16x32_bf16 v[68:71], v[202:205], v[194:197], v[68:71]
	v_mfma_f32_16x16x32_bf16 v[64:67], v[210:213], v[194:197], v[64:67]
	v_mfma_f32_16x16x32_bf16 v[92:95], v[206:209], v[170:173], v[92:95]
	v_mfma_f32_16x16x32_bf16 v[88:91], v[214:217], v[170:173], v[88:91]
	v_mfma_f32_16x16x32_bf16 v[84:87], v[206:209], v[178:181], v[84:87]
	v_mfma_f32_16x16x32_bf16 v[80:83], v[214:217], v[178:181], v[80:83]
	v_mfma_f32_16x16x32_bf16 v[76:79], v[206:209], v[186:189], v[76:79]
	v_mfma_f32_16x16x32_bf16 v[72:75], v[214:217], v[186:189], v[72:75]
	v_mfma_f32_16x16x32_bf16 v[68:71], v[206:209], v[198:201], v[68:71]
	v_mfma_f32_16x16x32_bf16 v[64:67], v[214:217], v[198:201], v[64:67]
	s_setprio 0
	s_mov_b32 m0, s52
	v_lshl_add_u64 v[190:191], v[220:221], 0, s[14:15]
	s_barrier
	ds_read_b128 v[166:169], v149 offset:49152
	ds_read_b128 v[170:173], v149 offset:50176
	ds_read_b128 v[174:177], v149 offset:51200
	ds_read_b128 v[178:181], v149 offset:52224
	ds_read_b128 v[182:185], v149 offset:53248
	ds_read_b128 v[186:189], v149 offset:54272
	ds_read_b128 v[194:197], v149 offset:55296
	ds_read_b128 v[198:201], v149 offset:56320
	global_load_lds_dwordx4 v[190:191], off
	v_lshl_add_u64 v[190:191], v[222:223], 0, s[14:15]
	s_mov_b32 m0, s53
	s_nop 0
	global_load_lds_dwordx4 v[190:191], off
	s_barrier
; __device__ __forceinline__ unsigned cvt_pk_bf16(float lo, float hi) { unsigned r; asm volatile("v_cvt_pk_bf16_f32 %0, %1, %2" : "=v"(r) : "v"(lo), "v"(hi)); return r; }
; #define PG8_STAGE(bufoff, gbase, voff) do { _Pragma("unroll") for (int _i = 0; _i < 2; ++_i) \
;         __builtin_amdgcn_global_load_lds((const unsigned*)((const char*)(gbase) + (voff)[_i]), (LAS unsigned*)(lds + (bufoff) + ldsw + _i * 8192), 16, 0, 0); } while (0)
; #define PG8_MMA(ai, bj, At, Bt) do { __builtin_amdgcn_s_setprio(1); _Pragma("unroll") for (int m = 0; m < 4; ++m) _Pragma("unroll") for (int n = 0; n < 2; ++n) _Pragma("unroll") for (int k = 0; k < 2; ++k) \
;         acc[ai][bj][m][n] = __builtin_amdgcn_mfma_f32_16x16x32_bf16(Bt[n][k], At[m][k], acc[ai][bj][m][n], 0, 0, 0); __builtin_amdgcn_s_setprio(0); } while (0)
; #define PG8_WAIT_V(n) asm volatile("s_waitcnt vmcnt(" #n ")" ::: "memory")
; #define PG8_WAIT_L(n) asm volatile("s_waitcnt lgkmcnt(" #n ")" ::: "memory")
; #define PG8_BAR __builtin_amdgcn_s_barrier()
; #define PG8_SCHED __builtin_amdgcn_sched_barrier(0)
; template <class Epi>
; __device__ __forceinline__ void gemm_phase(LAS unsigned char* lds, const Gemm g, const Sched& S, const Epi& E) {
;     ...
;             PG8_BAR; PG8_WAIT_L(0); PG8_MMA(1, 0, At, B0); PG8_BAR; PG8_SCHED;
;             PG8_STAGE(PG8_SB(1, 1), b3 + hstepB, voffB);
;             PG8_WAIT_V(6); PG8_BAR; PG8_MMA(1, 1, At, B1); PG8_BAR;
;     __device__ __forceinline__ void operator()(AccRef acc, const Unit& u, int wr, int wc, int fr, int fq) const {
;     ...
;             for (int m = 0; m < 4; ++m) { const size_t row = (size_t)u.pm * 256 + ai * 128 + wr * 64 + m * 16 + fr; float o[8];
; #pragma unroll
;                 for (int bj = 0; bj < 2; ++bj) { const f32x4 gg = acc[ai][bj][m][0], uu = acc[ai][bj][m][1];
; #pragma unroll
;                     for (int j = 0; j < 4; ++j) o[4 * bj + j] = gg[j] * __builtin_amdgcn_rcpf(1.0f + __expf(-gg[j])) * uu[j]; }
;                 u32x4 w; w.x = cvt_pk_bf16(o[0], o[1]); w.y = cvt_pk_bf16(o[2], o[3]); w.z = cvt_pk_bf16(o[4], o[5]); w.w = cvt_pk_bf16(o[6], o[7]);
;                 *(u32x4*)(act + row * FF_ + (u.pn * 4 + wc) * 32 + 8 * fq) = w; }
	s_waitcnt lgkmcnt(0)
	s_setprio 1
	s_waitcnt lgkmcnt(0)
	v_mfma_f32_16x16x32_bf16 v[60:63], v[150:153], v[166:169], v[60:63]
	v_mfma_f32_16x16x32_bf16 v[56:59], v[158:161], v[166:169], v[56:59]
	v_mfma_f32_16x16x32_bf16 v[52:55], v[150:153], v[174:177], v[52:55]
	v_mfma_f32_16x16x32_bf16 v[48:51], v[158:161], v[174:177], v[48:51]
	v_mfma_f32_16x16x32_bf16 v[44:47], v[150:153], v[182:185], v[44:47]
	v_mfma_f32_16x16x32_bf16 v[40:43], v[158:161], v[182:185], v[40:43]
	v_mfma_f32_16x16x32_bf16 v[36:39], v[150:153], v[194:197], v[36:39]
	v_mfma_f32_16x16x32_bf16 v[32:35], v[158:161], v[194:197], v[32:35]
	v_mfma_f32_16x16x32_bf16 v[60:63], v[154:157], v[170:173], v[60:63]
	v_mfma_f32_16x16x32_bf16 v[56:59], v[162:165], v[170:173], v[56:59]
	v_mfma_f32_16x16x32_bf16 v[52:55], v[154:157], v[178:181], v[52:55]
	v_mfma_f32_16x16x32_bf16 v[48:51], v[162:165], v[178:181], v[48:51]
	v_mfma_f32_16x16x32_bf16 v[44:47], v[154:157], v[186:189], v[44:47]
	v_mfma_f32_16x16x32_bf16 v[40:43], v[162:165], v[186:189], v[40:43]
	v_mfma_f32_16x16x32_bf16 v[36:39], v[154:157], v[198:201], v[36:39]
	v_mfma_f32_16x16x32_bf16 v[32:35], v[162:165], v[198:201], v[32:35]
	s_setprio 0
	s_barrier
	s_add_u32 s36, s36, 0x80080
	s_addc_u32 s37, s37, 0
	s_add_i32 s38, s38, s34
	v_lshl_add_u64 v[150:151], s[36:37], 0, v[130:131]
	s_mov_b32 m0, s38
	s_nop 0
	global_load_lds_dwordx4 v[150:151], off
	v_lshl_add_u64 v[150:151], s[36:37], 0, v[128:129]
	s_add_i32 m0, s38, 0x2000
	s_nop 0
	global_load_lds_dwordx4 v[150:151], off
	s_waitcnt vmcnt(6)
	s_barrier
	s_setprio 1
	v_mfma_f32_16x16x32_bf16 v[28:31], v[202:205], v[166:169], v[28:31]
	v_mfma_f32_16x16x32_bf16 v[24:27], v[210:213], v[166:169], v[24:27]
	v_mfma_f32_16x16x32_bf16 v[20:23], v[202:205], v[174:177], v[20:23]
	v_mfma_f32_16x16x32_bf16 v[16:19], v[210:213], v[174:177], v[16:19]
	v_mfma_f32_16x16x32_bf16 v[12:15], v[202:205], v[182:185], v[12:15]
	v_mfma_f32_16x16x32_bf16 v[8:11], v[210:213], v[182:185], v[8:11]
	v_mfma_f32_16x16x32_bf16 v[4:7], v[202:205], v[194:197], v[4:7]
	v_mfma_f32_16x16x32_bf16 v[0:3], v[210:213], v[194:197], v[0:3]
	v_mfma_f32_16x16x32_bf16 v[28:31], v[206:209], v[170:173], v[28:31]
	v_mfma_f32_16x16x32_bf16 v[24:27], v[214:217], v[170:173], v[24:27]
	v_mfma_f32_16x16x32_bf16 v[20:23], v[206:209], v[178:181], v[20:23]
	v_mfma_f32_16x16x32_bf16 v[16:19], v[214:217], v[178:181], v[16:19]
	v_mfma_f32_16x16x32_bf16 v[12:15], v[206:209], v[186:189], v[12:15]
	v_mfma_f32_16x16x32_bf16 v[8:11], v[214:217], v[186:189], v[8:11]
	v_mfma_f32_16x16x32_bf16 v[4:7], v[206:209], v[198:201], v[4:7]
	v_mfma_f32_16x16x32_bf16 v[0:3], v[214:217], v[198:201], v[0:3]
	s_setprio 0
	s_add_i32 s67, s67, 2
	s_add_u32 s24, s24, 0x100
	s_addc_u32 s25, s25, 0
	s_cmp_gt_u32 s67, 29
	s_barrier
	s_cbranch_scc0 .LBB0_3085
	v_mov_b32_e32 v170, 0xbfb8aa3b
	v_mov_b32_e32 v172, 1.0
	v_mov_b64_e32 v[176:177], 0
	v_mov_b64_e32 v[178:179], 0
	s_add_u32 s24, s11, 0xffffff00
	s_addc_u32 s25, s64, -1
	s_ashr_i32 s11, s10, 31
	s_lshl_b64 s[36:37], s[10:11], 8
	v_lshl_add_u64 v[144:145], v[134:135], 0, s[36:37]
	v_mov_b64_e32 v[146:147], s[44:45]
	v_mad_u64_u32 v[146:147], s[38:39], v144, s56, v[146:147]
	s_lshl_b32 s11, s50, 7
	v_mov_b32_e32 v144, v147
	s_or_b32 s36, s11, s51
	v_mad_u64_u32 v[144:145], s[38:39], v145, s56, v[144:145]
	s_ashr_i32 s37, s36, 31
	v_mov_b32_e32 v147, v144
	v_lshl_add_u64 v[144:145], s[36:37], 1, v[146:147]
	v_lshl_add_u64 v[144:145], v[144:145], 0, v[132:133]
	v_pk_mul_f32 v[162:163], v[124:125], v[170:171] op_sel_hi:[1,0]
	v_pk_mul_f32 v[164:165], v[126:127], v[170:171] op_sel_hi:[1,0]
	v_pk_mul_f32 v[166:167], v[92:93], v[170:171] op_sel_hi:[1,0]
	v_pk_mul_f32 v[168:169], v[94:95], v[170:171] op_sel_hi:[1,0]
	v_exp_f32_e32 v162, v162
	v_exp_f32_e32 v163, v163
	v_exp_f32_e32 v164, v164
	v_exp_f32_e32 v165, v165
	v_exp_f32_e32 v166, v166
	v_exp_f32_e32 v167, v167
	v_exp_f32_e32 v168, v168
	v_exp_f32_e32 v169, v169
	v_pk_add_f32 v[162:163], v[162:163], v[172:173] op_sel_hi:[1,0]
	v_pk_add_f32 v[164:165], v[164:165], v[172:173] op_sel_hi:[1,0]
	v_pk_add_f32 v[166:167], v[166:167], v[172:173] op_sel_hi:[1,0]
	v_pk_add_f32 v[168:169], v[168:169], v[172:173] op_sel_hi:[1,0]
	v_rcp_f32_e32 v162, v162
	v_rcp_f32_e32 v163, v163
	v_rcp_f32_e32 v164, v164
	v_rcp_f32_e32 v165, v165
	v_rcp_f32_e32 v166, v166
	v_rcp_f32_e32 v167, v167
	v_rcp_f32_e32 v168, v168
	v_rcp_f32_e32 v169, v169
	v_pk_mul_f32 v[162:163], v[124:125], v[162:163]
	v_pk_mul_f32 v[164:165], v[126:127], v[164:165]
	v_pk_mul_f32 v[166:167], v[92:93], v[166:167]
	v_pk_mul_f32 v[168:169], v[94:95], v[168:169]
	v_pk_mul_f32 v[162:163], v[120:121], v[162:163]
	v_pk_mul_f32 v[164:165], v[122:123], v[164:165]
	v_pk_mul_f32 v[166:167], v[88:89], v[166:167]
	v_pk_mul_f32 v[168:169], v[90:91], v[168:169]
	v_cvt_pk_bf16_f32 v150, v162, v163
	v_cvt_pk_bf16_f32 v151, v164, v165
	v_cvt_pk_bf16_f32 v152, v166, v167
	v_cvt_pk_bf16_f32 v153, v168, v169
	global_store_dwordx4 v[144:145], v[150:153], off
	v_add_co_u32_e32 v146, vcc, s57, v144
	s_nop 0
	v_addc_co_u32_e32 v147, vcc, 0, v145, vcc
	v_pk_mul_f32 v[162:163], v[116:117], v[170:171] op_sel_hi:[1,0]
	v_pk_mul_f32 v[164:165], v[118:119], v[170:171] op_sel_hi:[1,0]
	v_pk_mul_f32 v[166:167], v[84:85], v[170:171] op_sel_hi:[1,0]
	v_pk_mul_f32 v[168:169], v[86:87], v[170:171] op_sel_hi:[1,0]
	v_exp_f32_e32 v162, v162
	v_exp_f32_e32 v163, v163
	v_exp_f32_e32 v164, v164
	v_exp_f32_e32 v165, v165
	v_exp_f32_e32 v166, v166
	v_exp_f32_e32 v167, v167
	v_exp_f32_e32 v168, v168
	v_exp_f32_e32 v169, v169
	v_pk_add_f32 v[162:163], v[162:163], v[172:173] op_sel_hi:[1,0]
	v_pk_add_f32 v[164:165], v[164:165], v[172:173] op_sel_hi:[1,0]
; __device__ __forceinline__ unsigned cvt_pk_bf16(float lo, float hi) { unsigned r; asm volatile("v_cvt_pk_bf16_f32 %0, %1, %2" : "=v"(r) : "v"(lo), "v"(hi)); return r; }
; template <class Epi>
; __device__ __forceinline__ void gemm_phase(LAS unsigned char* lds, const Gemm g, const Sched& S, const Epi& E) {
;     ...
; #pragma unroll
;         for (int a = 0; a < 2; ++a)
; #pragma unroll
;             for (int b = 0; b < 2; ++b)
; #pragma unroll
;                 for (int m = 0; m < 4; ++m)
; #pragma unroll
;                     for (int n = 0; n < 2; ++n) acc[a][b][m][n] = (f32x4){0.f, 0.f, 0.f, 0.f};
;     __device__ __forceinline__ void operator()(AccRef acc, const Unit& u, int wr, int wc, int fr, int fq) const {
;     ...
;             for (int m = 0; m < 4; ++m) { const size_t row = (size_t)u.pm * 256 + ai * 128 + wr * 64 + m * 16 + fr; float o[8];
; #pragma unroll
;                 for (int bj = 0; bj < 2; ++bj) { const f32x4 gg = acc[ai][bj][m][0], uu = acc[ai][bj][m][1];
; #pragma unroll
;                     for (int j = 0; j < 4; ++j) o[4 * bj + j] = gg[j] * __builtin_amdgcn_rcpf(1.0f + __expf(-gg[j])) * uu[j]; }
;                 u32x4 w; w.x = cvt_pk_bf16(o[0], o[1]); w.y = cvt_pk_bf16(o[2], o[3]); w.z = cvt_pk_bf16(o[4], o[5]); w.w = cvt_pk_bf16(o[6], o[7]);
;                 *(u32x4*)(act + row * FF_ + (u.pn * 4 + wc) * 32 + 8 * fq) = w; }
	v_pk_add_f32 v[166:167], v[166:167], v[172:173] op_sel_hi:[1,0]
	v_pk_add_f32 v[168:169], v[168:169], v[172:173] op_sel_hi:[1,0]
	v_rcp_f32_e32 v162, v162
	v_rcp_f32_e32 v163, v163
	v_rcp_f32_e32 v164, v164
	v_rcp_f32_e32 v165, v165
	v_rcp_f32_e32 v166, v166
	v_rcp_f32_e32 v167, v167
	v_rcp_f32_e32 v168, v168
	v_rcp_f32_e32 v169, v169
	v_pk_mul_f32 v[162:163], v[116:117], v[162:163]
	v_pk_mul_f32 v[164:165], v[118:119], v[164:165]
	v_pk_mul_f32 v[166:167], v[84:85], v[166:167]
	v_pk_mul_f32 v[168:169], v[86:87], v[168:169]
	v_pk_mul_f32 v[162:163], v[112:113], v[162:163]
	v_pk_mul_f32 v[164:165], v[114:115], v[164:165]
	v_pk_mul_f32 v[166:167], v[80:81], v[166:167]
	v_pk_mul_f32 v[168:169], v[82:83], v[168:169]
	v_cvt_pk_bf16_f32 v150, v162, v163
	v_cvt_pk_bf16_f32 v151, v164, v165
	v_cvt_pk_bf16_f32 v152, v166, v167
	v_cvt_pk_bf16_f32 v153, v168, v169
	global_store_dwordx4 v[146:147], v[150:153], off
	v_mfma_f32_32x32x16_bf16 v[80:95], v[176:179], v[176:179], 0
	v_mfma_f32_32x32x16_bf16 v[112:127], v[176:179], v[176:179], 0
	v_add_co_u32_e32 v146, vcc, s58, v144
	s_nop 0
	v_addc_co_u32_e32 v147, vcc, 0, v145, vcc
	v_pk_mul_f32 v[162:163], v[108:109], v[170:171] op_sel_hi:[1,0]
	v_pk_mul_f32 v[164:165], v[110:111], v[170:171] op_sel_hi:[1,0]
	v_pk_mul_f32 v[166:167], v[76:77], v[170:171] op_sel_hi:[1,0]
	v_pk_mul_f32 v[168:169], v[78:79], v[170:171] op_sel_hi:[1,0]
	v_exp_f32_e32 v162, v162
	v_exp_f32_e32 v163, v163
	v_exp_f32_e32 v164, v164
	v_exp_f32_e32 v165, v165
	v_exp_f32_e32 v166, v166
	v_exp_f32_e32 v167, v167
	v_exp_f32_e32 v168, v168
	v_exp_f32_e32 v169, v169
	v_pk_add_f32 v[162:163], v[162:163], v[172:173] op_sel_hi:[1,0]
	v_pk_add_f32 v[164:165], v[164:165], v[172:173] op_sel_hi:[1,0]
	v_pk_add_f32 v[166:167], v[166:167], v[172:173] op_sel_hi:[1,0]
	v_pk_add_f32 v[168:169], v[168:169], v[172:173] op_sel_hi:[1,0]
	v_rcp_f32_e32 v162, v162
	v_rcp_f32_e32 v163, v163
	v_rcp_f32_e32 v164, v164
	v_rcp_f32_e32 v165, v165
	v_rcp_f32_e32 v166, v166
	v_rcp_f32_e32 v167, v167
	v_rcp_f32_e32 v168, v168
	v_rcp_f32_e32 v169, v169
	v_pk_mul_f32 v[162:163], v[108:109], v[162:163]
	v_pk_mul_f32 v[164:165], v[110:111], v[164:165]
	v_pk_mul_f32 v[166:167], v[76:77], v[166:167]
	v_pk_mul_f32 v[168:169], v[78:79], v[168:169]
	v_pk_mul_f32 v[162:163], v[104:105], v[162:163]
	v_pk_mul_f32 v[164:165], v[106:107], v[164:165]
	v_pk_mul_f32 v[166:167], v[72:73], v[166:167]
	v_pk_mul_f32 v[168:169], v[74:75], v[168:169]
	v_cvt_pk_bf16_f32 v150, v162, v163
	v_cvt_pk_bf16_f32 v151, v164, v165
	v_cvt_pk_bf16_f32 v152, v166, v167
	v_cvt_pk_bf16_f32 v153, v168, v169
	global_store_dwordx4 v[146:147], v[150:153], off
	v_add_co_u32_e32 v146, vcc, s59, v144
	s_nop 0
	v_addc_co_u32_e32 v147, vcc, 0, v145, vcc
	v_pk_mul_f32 v[162:163], v[100:101], v[170:171] op_sel_hi:[1,0]
	v_pk_mul_f32 v[164:165], v[102:103], v[170:171] op_sel_hi:[1,0]
	v_pk_mul_f32 v[166:167], v[68:69], v[170:171] op_sel_hi:[1,0]
	v_pk_mul_f32 v[168:169], v[70:71], v[170:171] op_sel_hi:[1,0]
	v_exp_f32_e32 v162, v162
	v_exp_f32_e32 v163, v163
	v_exp_f32_e32 v164, v164
	v_exp_f32_e32 v165, v165
	v_exp_f32_e32 v166, v166
	v_exp_f32_e32 v167, v167
	v_exp_f32_e32 v168, v168
	v_exp_f32_e32 v169, v169
	v_pk_add_f32 v[162:163], v[162:163], v[172:173] op_sel_hi:[1,0]
	v_pk_add_f32 v[164:165], v[164:165], v[172:173] op_sel_hi:[1,0]
	v_pk_add_f32 v[166:167], v[166:167], v[172:173] op_sel_hi:[1,0]
	v_pk_add_f32 v[168:169], v[168:169], v[172:173] op_sel_hi:[1,0]
	v_rcp_f32_e32 v162, v162
	v_rcp_f32_e32 v163, v163
	v_rcp_f32_e32 v164, v164
	v_rcp_f32_e32 v165, v165
	v_rcp_f32_e32 v166, v166
	v_rcp_f32_e32 v167, v167
	v_rcp_f32_e32 v168, v168
	v_rcp_f32_e32 v169, v169
	v_pk_mul_f32 v[162:163], v[100:101], v[162:163]
	v_pk_mul_f32 v[164:165], v[102:103], v[164:165]
	v_pk_mul_f32 v[166:167], v[68:69], v[166:167]
	v_pk_mul_f32 v[168:169], v[70:71], v[168:169]
	v_pk_mul_f32 v[162:163], v[96:97], v[162:163]
	v_pk_mul_f32 v[164:165], v[98:99], v[164:165]
	v_pk_mul_f32 v[166:167], v[64:65], v[166:167]
	v_pk_mul_f32 v[168:169], v[66:67], v[168:169]
	v_cvt_pk_bf16_f32 v150, v162, v163
	v_cvt_pk_bf16_f32 v151, v164, v165
	v_cvt_pk_bf16_f32 v152, v166, v167
	v_cvt_pk_bf16_f32 v153, v168, v169
	global_store_dwordx4 v[146:147], v[150:153], off
	v_mfma_f32_32x32x16_bf16 v[64:79], v[176:179], v[176:179], 0
	v_mfma_f32_32x32x16_bf16 v[96:111], v[176:179], v[176:179], 0
	v_add_co_u32_e32 v146, vcc, s60, v144
	s_nop 0
	v_addc_co_u32_e32 v147, vcc, 0, v145, vcc
	v_pk_mul_f32 v[162:163], v[60:61], v[170:171] op_sel_hi:[1,0]
	v_pk_mul_f32 v[164:165], v[62:63], v[170:171] op_sel_hi:[1,0]
	v_pk_mul_f32 v[166:167], v[28:29], v[170:171] op_sel_hi:[1,0]
	v_pk_mul_f32 v[168:169], v[30:31], v[170:171] op_sel_hi:[1,0]
	v_exp_f32_e32 v162, v162
	v_exp_f32_e32 v163, v163
	v_exp_f32_e32 v164, v164
	v_exp_f32_e32 v165, v165
	v_exp_f32_e32 v166, v166
	v_exp_f32_e32 v167, v167
	v_exp_f32_e32 v168, v168
	v_exp_f32_e32 v169, v169
	v_pk_add_f32 v[162:163], v[162:163], v[172:173] op_sel_hi:[1,0]
	v_pk_add_f32 v[164:165], v[164:165], v[172:173] op_sel_hi:[1,0]
	v_pk_add_f32 v[166:167], v[166:167], v[172:173] op_sel_hi:[1,0]
	v_pk_add_f32 v[168:169], v[168:169], v[172:173] op_sel_hi:[1,0]
	v_rcp_f32_e32 v162, v162
	v_rcp_f32_e32 v163, v163
	v_rcp_f32_e32 v164, v164
	v_rcp_f32_e32 v165, v165
	v_rcp_f32_e32 v166, v166
	v_rcp_f32_e32 v167, v167
	v_rcp_f32_e32 v168, v168
	v_rcp_f32_e32 v169, v169
	v_pk_mul_f32 v[162:163], v[60:61], v[162:163]
	v_pk_mul_f32 v[164:165], v[62:63], v[164:165]
	v_pk_mul_f32 v[166:167], v[28:29], v[166:167]
	v_pk_mul_f32 v[168:169], v[30:31], v[168:169]
; __device__ __forceinline__ unsigned cvt_pk_bf16(float lo, float hi) { unsigned r; asm volatile("v_cvt_pk_bf16_f32 %0, %1, %2" : "=v"(r) : "v"(lo), "v"(hi)); return r; }
; template <class Epi>
; __device__ __forceinline__ void gemm_phase(LAS unsigned char* lds, const Gemm g, const Sched& S, const Epi& E) {
;     ...
;         if (!has_next) break;
; #pragma unroll
;         for (int a = 0; a < 2; ++a)
; #pragma unroll
;             for (int b = 0; b < 2; ++b)
; #pragma unroll
;                 for (int m = 0; m < 4; ++m)
; #pragma unroll
;                     for (int n = 0; n < 2; ++n) acc[a][b][m][n] = (f32x4){0.f, 0.f, 0.f, 0.f};
;         cur = nxt; cA = nA; cB = nB; ++ui;
;     __device__ __forceinline__ void operator()(AccRef acc, const Unit& u, int wr, int wc, int fr, int fq) const {
;     ...
;             for (int m = 0; m < 4; ++m) { const size_t row = (size_t)u.pm * 256 + ai * 128 + wr * 64 + m * 16 + fr; float o[8];
; #pragma unroll
;                 for (int bj = 0; bj < 2; ++bj) { const f32x4 gg = acc[ai][bj][m][0], uu = acc[ai][bj][m][1];
; #pragma unroll
;                     for (int j = 0; j < 4; ++j) o[4 * bj + j] = gg[j] * __builtin_amdgcn_rcpf(1.0f + __expf(-gg[j])) * uu[j]; }
;                 u32x4 w; w.x = cvt_pk_bf16(o[0], o[1]); w.y = cvt_pk_bf16(o[2], o[3]); w.z = cvt_pk_bf16(o[4], o[5]); w.w = cvt_pk_bf16(o[6], o[7]);
;                 *(u32x4*)(act + row * FF_ + (u.pn * 4 + wc) * 32 + 8 * fq) = w; }
	v_pk_mul_f32 v[162:163], v[56:57], v[162:163]
	v_pk_mul_f32 v[164:165], v[58:59], v[164:165]
	v_pk_mul_f32 v[166:167], v[24:25], v[166:167]
	v_pk_mul_f32 v[168:169], v[26:27], v[168:169]
	v_cvt_pk_bf16_f32 v150, v162, v163
	v_cvt_pk_bf16_f32 v151, v164, v165
	v_cvt_pk_bf16_f32 v152, v166, v167
	v_cvt_pk_bf16_f32 v153, v168, v169
	global_store_dwordx4 v[146:147], v[150:153], off
	v_add_co_u32_e32 v146, vcc, s61, v144
	s_nop 0
	v_addc_co_u32_e32 v147, vcc, 0, v145, vcc
	v_pk_mul_f32 v[162:163], v[52:53], v[170:171] op_sel_hi:[1,0]
	v_pk_mul_f32 v[164:165], v[54:55], v[170:171] op_sel_hi:[1,0]
	v_pk_mul_f32 v[166:167], v[20:21], v[170:171] op_sel_hi:[1,0]
	v_pk_mul_f32 v[168:169], v[22:23], v[170:171] op_sel_hi:[1,0]
	v_exp_f32_e32 v162, v162
	v_exp_f32_e32 v163, v163
	v_exp_f32_e32 v164, v164
	v_exp_f32_e32 v165, v165
	v_exp_f32_e32 v166, v166
	v_exp_f32_e32 v167, v167
	v_exp_f32_e32 v168, v168
	v_exp_f32_e32 v169, v169
	v_pk_add_f32 v[162:163], v[162:163], v[172:173] op_sel_hi:[1,0]
	v_pk_add_f32 v[164:165], v[164:165], v[172:173] op_sel_hi:[1,0]
	v_pk_add_f32 v[166:167], v[166:167], v[172:173] op_sel_hi:[1,0]
	v_pk_add_f32 v[168:169], v[168:169], v[172:173] op_sel_hi:[1,0]
	v_rcp_f32_e32 v162, v162
	v_rcp_f32_e32 v163, v163
	v_rcp_f32_e32 v164, v164
	v_rcp_f32_e32 v165, v165
	v_rcp_f32_e32 v166, v166
	v_rcp_f32_e32 v167, v167
	v_rcp_f32_e32 v168, v168
	v_rcp_f32_e32 v169, v169
	v_pk_mul_f32 v[162:163], v[52:53], v[162:163]
	v_pk_mul_f32 v[164:165], v[54:55], v[164:165]
	v_pk_mul_f32 v[166:167], v[20:21], v[166:167]
	v_pk_mul_f32 v[168:169], v[22:23], v[168:169]
	v_pk_mul_f32 v[162:163], v[48:49], v[162:163]
	v_pk_mul_f32 v[164:165], v[50:51], v[164:165]
	v_pk_mul_f32 v[166:167], v[16:17], v[166:167]
	v_pk_mul_f32 v[168:169], v[18:19], v[168:169]
	v_cvt_pk_bf16_f32 v150, v162, v163
	v_cvt_pk_bf16_f32 v151, v164, v165
	v_cvt_pk_bf16_f32 v152, v166, v167
	v_cvt_pk_bf16_f32 v153, v168, v169
	global_store_dwordx4 v[146:147], v[150:153], off
	v_mfma_f32_32x32x16_bf16 v[16:31], v[176:179], v[176:179], 0
	v_mfma_f32_32x32x16_bf16 v[48:63], v[176:179], v[176:179], 0
	v_add_co_u32_e32 v146, vcc, s62, v144
	s_nop 0
	v_addc_co_u32_e32 v147, vcc, 0, v145, vcc
	v_pk_mul_f32 v[162:163], v[44:45], v[170:171] op_sel_hi:[1,0]
	v_pk_mul_f32 v[164:165], v[46:47], v[170:171] op_sel_hi:[1,0]
	v_pk_mul_f32 v[166:167], v[12:13], v[170:171] op_sel_hi:[1,0]
	v_pk_mul_f32 v[168:169], v[14:15], v[170:171] op_sel_hi:[1,0]
	v_exp_f32_e32 v162, v162
	v_exp_f32_e32 v163, v163
	v_exp_f32_e32 v164, v164
	v_exp_f32_e32 v165, v165
	v_exp_f32_e32 v166, v166
	v_exp_f32_e32 v167, v167
	v_exp_f32_e32 v168, v168
	v_exp_f32_e32 v169, v169
	v_pk_add_f32 v[162:163], v[162:163], v[172:173] op_sel_hi:[1,0]
	v_pk_add_f32 v[164:165], v[164:165], v[172:173] op_sel_hi:[1,0]
	v_pk_add_f32 v[166:167], v[166:167], v[172:173] op_sel_hi:[1,0]
	v_pk_add_f32 v[168:169], v[168:169], v[172:173] op_sel_hi:[1,0]
	v_rcp_f32_e32 v162, v162
	v_rcp_f32_e32 v163, v163
	v_rcp_f32_e32 v164, v164
	v_rcp_f32_e32 v165, v165
	v_rcp_f32_e32 v166, v166
	v_rcp_f32_e32 v167, v167
	v_rcp_f32_e32 v168, v168
	v_rcp_f32_e32 v169, v169
	v_pk_mul_f32 v[162:163], v[44:45], v[162:163]
	v_pk_mul_f32 v[164:165], v[46:47], v[164:165]
	v_pk_mul_f32 v[166:167], v[12:13], v[166:167]
	v_pk_mul_f32 v[168:169], v[14:15], v[168:169]
	v_pk_mul_f32 v[162:163], v[40:41], v[162:163]
	v_pk_mul_f32 v[164:165], v[42:43], v[164:165]
	v_pk_mul_f32 v[166:167], v[8:9], v[166:167]
	v_pk_mul_f32 v[168:169], v[10:11], v[168:169]
	v_cvt_pk_bf16_f32 v150, v162, v163
	v_cvt_pk_bf16_f32 v151, v164, v165
	v_cvt_pk_bf16_f32 v152, v166, v167
	v_cvt_pk_bf16_f32 v153, v168, v169
	global_store_dwordx4 v[146:147], v[150:153], off
	v_add_co_u32_e32 v144, vcc, 0x1e4000, v144
	v_addc_co_u32_e32 v145, vcc, 0, v145, vcc
	s_andn2_b64 vcc, exec, s[8:9]
	v_pk_mul_f32 v[162:163], v[36:37], v[170:171] op_sel_hi:[1,0]
	v_pk_mul_f32 v[164:165], v[38:39], v[170:171] op_sel_hi:[1,0]
	v_pk_mul_f32 v[166:167], v[4:5], v[170:171] op_sel_hi:[1,0]
	v_pk_mul_f32 v[168:169], v[6:7], v[170:171] op_sel_hi:[1,0]
	v_exp_f32_e32 v162, v162
	v_exp_f32_e32 v163, v163
	v_exp_f32_e32 v164, v164
	v_exp_f32_e32 v165, v165
	v_exp_f32_e32 v166, v166
	v_exp_f32_e32 v167, v167
	v_exp_f32_e32 v168, v168
	v_exp_f32_e32 v169, v169
	v_pk_add_f32 v[162:163], v[162:163], v[172:173] op_sel_hi:[1,0]
	v_pk_add_f32 v[164:165], v[164:165], v[172:173] op_sel_hi:[1,0]
	v_pk_add_f32 v[166:167], v[166:167], v[172:173] op_sel_hi:[1,0]
	v_pk_add_f32 v[168:169], v[168:169], v[172:173] op_sel_hi:[1,0]
	v_rcp_f32_e32 v162, v162
	v_rcp_f32_e32 v163, v163
	v_rcp_f32_e32 v164, v164
	v_rcp_f32_e32 v165, v165
	v_rcp_f32_e32 v166, v166
	v_rcp_f32_e32 v167, v167
	v_rcp_f32_e32 v168, v168
	v_rcp_f32_e32 v169, v169
	v_pk_mul_f32 v[162:163], v[36:37], v[162:163]
	v_pk_mul_f32 v[164:165], v[38:39], v[164:165]
	v_pk_mul_f32 v[166:167], v[4:5], v[166:167]
	v_pk_mul_f32 v[168:169], v[6:7], v[168:169]
	v_pk_mul_f32 v[162:163], v[32:33], v[162:163]
	v_pk_mul_f32 v[164:165], v[34:35], v[164:165]
	v_pk_mul_f32 v[166:167], v[0:1], v[166:167]
	v_pk_mul_f32 v[168:169], v[2:3], v[168:169]
	v_cvt_pk_bf16_f32 v150, v162, v163
	v_cvt_pk_bf16_f32 v151, v164, v165
	v_cvt_pk_bf16_f32 v152, v166, v167
	v_cvt_pk_bf16_f32 v153, v168, v169
	global_store_dwordx4 v[144:145], v[150:153], off
	v_mfma_f32_32x32x16_bf16 v[0:15], v[176:179], v[176:179], 0
	v_mfma_f32_32x32x16_bf16 v[32:47], v[176:179], v[176:179], 0
	s_cbranch_vccz .LBB0_3081
	s_mov_b64 s[20:21], s[24:25]
	s_andn2_b64 vcc, exec, s[6:7]
	s_mov_b64 s[24:25], s[20:21]
	s_cbranch_vccnz .LBB0_3082
